# GEMM loops: loop-top load segment issues its LDS fragment reads first (invariant addresses), loop-control SALU moved into the previous MFMA segment tail, and each MFMA segment signals its closing barr
# speedup vs baseline: 1.0136x; 1.0059x over previous
; #define PG8_STAGE(bufoff, gbase, voff) do { _Pragma("unroll") for (int _i = 0; _i < 2; ++_i) \
;         __builtin_amdgcn_global_load_lds((const unsigned*)((const char*)(gbase) + (voff)[_i]), (LAS unsigned*)(lds + (bufoff) + ldsw + _i * 8192), 16, 0, 0); } while (0)
; #define PG8_LDA(dst, b, h) do { _Pragma("unroll") for (int m = 0; m < 4; ++m) _Pragma("unroll") for (int k = 0; k < 2; ++k) dst[m][k] = *(const LAS bf16x8*)(lds + PG8_SA(b, h) + aoff + m * 2048 + k * 1024); } while (0)
; #define PG8_LDB(dst, b, h) do { _Pragma("unroll") for (int n = 0; n < 2; ++n) _Pragma("unroll") for (int k = 0; k < 2; ++k) dst[n][k] = *(const LAS bf16x8*)(lds + PG8_SB(b, h) + boff + n * 2048 + k * 1024); } while (0)
; #define PG8_MMA(ai, bj, At, Bt) do { __builtin_amdgcn_s_setprio(1); _Pragma("unroll") for (int m = 0; m < 4; ++m) _Pragma("unroll") for (int n = 0; n < 2; ++n) _Pragma("unroll") for (int k = 0; k < 2; ++k) \
;         acc[ai][bj][m][n] = __builtin_amdgcn_mfma_f32_16x16x32_bf16(Bt[n][k], At[m][k], acc[ai][bj][m][n], 0, 0, 0); __builtin_amdgcn_s_setprio(0); } while (0)
; #define PG8_WAIT_V(n) asm volatile("s_waitcnt vmcnt(" #n ")" ::: "memory")
; #define PG8_WAIT_L(n) asm volatile("s_waitcnt lgkmcnt(" #n ")" ::: "memory")
; #define PG8_BAR __builtin_amdgcn_s_barrier()
; #define PG8_SCHED __builtin_amdgcn_sched_barrier(0)
; template <class Epi, bool KREV = false>
; __device__ __forceinline__ void gemm_phase(LAS unsigned char* lds, const Gemm g, const StaticOrder& S, const Epi& E, int wave_s) {
;     ...
;         for (int t = 0; t < nt; t += 2) {
;             const bool last = (t == nt - 2);
;             const char* a1 = cA + (size_t)(t + 1) * kstep;
;             const char* a2 = last ? nA : cA + (size_t)(t + 2) * kstep; const char* b2 = last ? nB : cB + (size_t)(t + 2) * kstep;
;             const char* a3 = a2 + kstep; const char* b3 = b2 + kstep;
;             PG8_LDB(B0, 0, 0); PG8_LDB(B1, 0, 1); PG8_SCHED; PG8_LDA(At, 0, 0); PG8_STAGE(PG8_SA(1, 1), a1 + hstep, voffA);
;             PG8_WAIT_V(8); PG8_WAIT_L(0); PG8_BAR; PG8_MMA(0, 0, At, B0); PG8_MMA(0, 1, At, B1); PG8_BAR; PG8_SCHED;
;             PG8_LDA(At, 0, 1); PG8_STAGE(PG8_SB(0, 0), b2, voffB); PG8_STAGE(PG8_SB(0, 1), b2 + bh, voffB); PG8_STAGE(PG8_SA(0, 0), a2, voffA);
;             PG8_WAIT_V(8); PG8_WAIT_L(0); PG8_BAR; PG8_MMA(1, 0, At, B0); PG8_MMA(1, 1, At, B1); PG8_BAR; PG8_SCHED;
.LBB0_162:
	v_add_u32_e32 v138, 0x10000, v140
	ds_read_b128 v[146:149], v138
	ds_read_b128 v[150:153], v138 offset:1024
	ds_read_b128 v[154:157], v138 offset:2048
	ds_read_b128 v[158:161], v138 offset:3072
	v_add_u32_e32 v138, 0x14000, v140
	ds_read_b128 v[162:165], v138
	ds_read_b128 v[166:169], v138 offset:1024
	ds_read_b128 v[170:173], v138 offset:2048
	ds_read_b128 v[178:181], v138 offset:3072
	ds_read_b128 v[182:185], v143
	ds_read_b128 v[186:189], v143 offset:1024
	ds_read_b128 v[190:193], v143 offset:2048
	ds_read_b128 v[194:197], v143 offset:3072
	ds_read_b128 v[198:201], v143 offset:4096
	ds_read_b128 v[202:205], v143 offset:5120
	ds_read_b128 v[218:221], v143 offset:6144
	ds_read_b128 v[222:225], v143 offset:7168
	s_add_u32 s24, s22, 0xfff80080
	s_addc_u32 s25, s23, -1
	s_add_i32 s50, 0, 0x10000
	s_cmp_eq_u32 s49, 28
	s_cselect_b32 s27, s43, s25
	s_cselect_b32 s26, s44, s24
	s_cselect_b32 s25, s45, s48
	s_cselect_b32 s24, s46, s47
	s_add_i32 s52, 0, 0x14000
	s_add_i32 m0, s9, 0xc000
	s_nop 0
	global_load_lds_dwordx4 v134, s[22:23]
	s_add_i32 m0, s9, 0xe000
	s_nop 0
	global_load_lds_dwordx4 v136, s[22:23]
	s_waitcnt vmcnt(8)
	s_waitcnt lgkmcnt(0)
	s_barrier
	s_setprio 1
	s_waitcnt lgkmcnt(0)
	v_mfma_f32_16x16x32_bf16 v[124:127], v[146:149], v[182:185], v[124:127]
	v_mfma_f32_16x16x32_bf16 v[120:123], v[154:157], v[182:185], v[120:123]
	v_mfma_f32_16x16x32_bf16 v[108:111], v[146:149], v[190:193], v[108:111]
	v_mfma_f32_16x16x32_bf16 v[104:107], v[154:157], v[190:193], v[104:107]
	v_mfma_f32_16x16x32_bf16 v[92:95], v[146:149], v[198:201], v[92:95]
	v_mfma_f32_16x16x32_bf16 v[88:91], v[154:157], v[198:201], v[88:91]
	v_mfma_f32_16x16x32_bf16 v[76:79], v[146:149], v[218:221], v[76:79]
	v_mfma_f32_16x16x32_bf16 v[72:75], v[154:157], v[218:221], v[72:75]
	v_mfma_f32_16x16x32_bf16 v[124:127], v[150:153], v[186:189], v[124:127]
	v_mfma_f32_16x16x32_bf16 v[120:123], v[158:161], v[186:189], v[120:123]
	v_mfma_f32_16x16x32_bf16 v[108:111], v[150:153], v[194:197], v[108:111]
	v_mfma_f32_16x16x32_bf16 v[104:107], v[158:161], v[194:197], v[104:107]
	v_mfma_f32_16x16x32_bf16 v[92:95], v[150:153], v[202:205], v[92:95]
	v_mfma_f32_16x16x32_bf16 v[88:91], v[158:161], v[202:205], v[88:91]
	v_mfma_f32_16x16x32_bf16 v[76:79], v[150:153], v[222:225], v[76:79]
	v_mfma_f32_16x16x32_bf16 v[72:75], v[158:161], v[222:225], v[72:75]
	s_setprio 0
	s_setprio 1
	v_mfma_f32_16x16x32_bf16 v[116:119], v[162:165], v[182:185], v[116:119]
	v_mfma_f32_16x16x32_bf16 v[112:115], v[170:173], v[182:185], v[112:115]
	v_mfma_f32_16x16x32_bf16 v[100:103], v[162:165], v[190:193], v[100:103]
	v_mfma_f32_16x16x32_bf16 v[96:99], v[170:173], v[190:193], v[96:99]
	v_mfma_f32_16x16x32_bf16 v[84:87], v[162:165], v[198:201], v[84:87]
	v_mfma_f32_16x16x32_bf16 v[80:83], v[170:173], v[198:201], v[80:83]
	v_mfma_f32_16x16x32_bf16 v[68:71], v[162:165], v[218:221], v[68:71]
	v_mfma_f32_16x16x32_bf16 v[64:67], v[170:173], v[218:221], v[64:67]
	v_mfma_f32_16x16x32_bf16 v[116:119], v[166:169], v[186:189], v[116:119]
	v_mfma_f32_16x16x32_bf16 v[112:115], v[178:181], v[186:189], v[112:115]
	v_mfma_f32_16x16x32_bf16 v[100:103], v[166:169], v[194:197], v[100:103]
	v_mfma_f32_16x16x32_bf16 v[96:99], v[178:181], v[194:197], v[96:99]
	v_mfma_f32_16x16x32_bf16 v[84:87], v[166:169], v[202:205], v[84:87]
	v_mfma_f32_16x16x32_bf16 v[80:83], v[178:181], v[202:205], v[80:83]
	v_mfma_f32_16x16x32_bf16 v[68:71], v[166:169], v[222:225], v[68:71]
	s_barrier
	v_mfma_f32_16x16x32_bf16 v[64:67], v[178:181], v[222:225], v[64:67]
	s_setprio 0
	s_add_u32 s98, s24, s2
	s_addc_u32 s99, s25, s3
	s_add_u32 s100, s26, s2
	s_addc_u32 s101, s27, s3
	s_add_i32 s50, s50, s29
	s_mov_b32 m0, s50
	ds_read_b128 v[182:185], v143 offset:16384
	ds_read_b128 v[186:189], v143 offset:17408
	ds_read_b128 v[190:193], v143 offset:18432
	ds_read_b128 v[194:197], v143 offset:19456
	ds_read_b128 v[198:201], v143 offset:20480
	ds_read_b128 v[202:205], v143 offset:21504
	ds_read_b128 v[218:221], v143 offset:22528
	ds_read_b128 v[222:225], v143 offset:23552
	global_load_lds_dwordx4 v176, s[24:25]
	s_add_i32 m0, s50, 0x2000
	s_add_u32 s50, s24, 0x80000
	s_addc_u32 s51, s25, 0
	s_add_i32 s52, s52, s29
	global_load_lds_dwordx4 v132, s[24:25]
	s_mov_b32 m0, s52
	v_lshl_add_u64 v[226:227], s[26:27], 0, v[130:131]
	global_load_lds_dwordx4 v176, s[50:51]
	s_add_i32 m0, s52, 0x2000
	s_nop 0
	global_load_lds_dwordx4 v132, s[50:51]
	s_mov_b32 m0, s9
	s_nop 0
	global_load_lds_dwordx4 v128, s[26:27]
	s_mov_b32 m0, s11
	s_nop 0
	global_load_lds_dwordx4 v130, s[26:27]
	s_waitcnt vmcnt(8)
	s_waitcnt lgkmcnt(0)
	s_barrier
; #define PG8_STAGE(bufoff, gbase, voff) do { _Pragma("unroll") for (int _i = 0; _i < 2; ++_i) \
;         __builtin_amdgcn_global_load_lds((const unsigned*)((const char*)(gbase) + (voff)[_i]), (LAS unsigned*)(lds + (bufoff) + ldsw + _i * 8192), 16, 0, 0); } while (0)
; #define PG8_LDA(dst, b, h) do { _Pragma("unroll") for (int m = 0; m < 4; ++m) _Pragma("unroll") for (int k = 0; k < 2; ++k) dst[m][k] = *(const LAS bf16x8*)(lds + PG8_SA(b, h) + aoff + m * 2048 + k * 1024); } while (0)
; #define PG8_LDB(dst, b, h) do { _Pragma("unroll") for (int n = 0; n < 2; ++n) _Pragma("unroll") for (int k = 0; k < 2; ++k) dst[n][k] = *(const LAS bf16x8*)(lds + PG8_SB(b, h) + boff + n * 2048 + k * 1024); } while (0)
; #define PG8_MMA(ai, bj, At, Bt) do { __builtin_amdgcn_s_setprio(1); _Pragma("unroll") for (int m = 0; m < 4; ++m) _Pragma("unroll") for (int n = 0; n < 2; ++n) _Pragma("unroll") for (int k = 0; k < 2; ++k) \
;         acc[ai][bj][m][n] = __builtin_amdgcn_mfma_f32_16x16x32_bf16(Bt[n][k], At[m][k], acc[ai][bj][m][n], 0, 0, 0); __builtin_amdgcn_s_setprio(0); } while (0)
; #define PG8_WAIT_V(n) asm volatile("s_waitcnt vmcnt(" #n ")" ::: "memory")
; #define PG8_WAIT_L(n) asm volatile("s_waitcnt lgkmcnt(" #n ")" ::: "memory")
; #define PG8_BAR __builtin_amdgcn_s_barrier()
; #define PG8_SCHED __builtin_amdgcn_sched_barrier(0)
; template <class Epi, bool KREV = false>
; __device__ __forceinline__ void gemm_phase(LAS unsigned char* lds, const Gemm g, const StaticOrder& S, const Epi& E, int wave_s) {
;     ...
;             PG8_WAIT_V(8); PG8_WAIT_L(0); PG8_BAR; PG8_MMA(1, 0, At, B0); PG8_MMA(1, 1, At, B1); PG8_BAR; PG8_SCHED;
;             PG8_LDB(B0, 1, 0); PG8_LDB(B1, 1, 1); PG8_SCHED; PG8_LDA(At, 1, 0); PG8_STAGE(PG8_SA(0, 1), a2 + hstep, voffA);
;             PG8_WAIT_V(8); PG8_WAIT_L(0); PG8_BAR; PG8_MMA(0, 0, At, B0); PG8_MMA(0, 1, At, B1); PG8_BAR; PG8_SCHED;
	s_setprio 1
	s_waitcnt lgkmcnt(0)
	v_mfma_f32_16x16x32_bf16 v[60:63], v[146:149], v[182:185], v[60:63]
	v_mfma_f32_16x16x32_bf16 v[56:59], v[154:157], v[182:185], v[56:59]
	v_mfma_f32_16x16x32_bf16 v[44:47], v[146:149], v[190:193], v[44:47]
	v_mfma_f32_16x16x32_bf16 v[40:43], v[154:157], v[190:193], v[40:43]
	v_mfma_f32_16x16x32_bf16 v[28:31], v[146:149], v[198:201], v[28:31]
	v_mfma_f32_16x16x32_bf16 v[24:27], v[154:157], v[198:201], v[24:27]
	v_mfma_f32_16x16x32_bf16 v[12:15], v[146:149], v[218:221], v[12:15]
	v_mfma_f32_16x16x32_bf16 v[8:11], v[154:157], v[218:221], v[8:11]
	v_mfma_f32_16x16x32_bf16 v[60:63], v[150:153], v[186:189], v[60:63]
	v_mfma_f32_16x16x32_bf16 v[56:59], v[158:161], v[186:189], v[56:59]
	v_mfma_f32_16x16x32_bf16 v[44:47], v[150:153], v[194:197], v[44:47]
	v_mfma_f32_16x16x32_bf16 v[40:43], v[158:161], v[194:197], v[40:43]
	v_mfma_f32_16x16x32_bf16 v[28:31], v[150:153], v[202:205], v[28:31]
	v_mfma_f32_16x16x32_bf16 v[24:27], v[158:161], v[202:205], v[24:27]
	v_mfma_f32_16x16x32_bf16 v[12:15], v[150:153], v[222:225], v[12:15]
	v_mfma_f32_16x16x32_bf16 v[8:11], v[158:161], v[222:225], v[8:11]
	s_setprio 0
	s_setprio 1
	v_mfma_f32_16x16x32_bf16 v[52:55], v[162:165], v[182:185], v[52:55]
	v_mfma_f32_16x16x32_bf16 v[48:51], v[170:173], v[182:185], v[48:51]
	v_mfma_f32_16x16x32_bf16 v[36:39], v[162:165], v[190:193], v[36:39]
	v_mfma_f32_16x16x32_bf16 v[32:35], v[170:173], v[190:193], v[32:35]
	v_mfma_f32_16x16x32_bf16 v[20:23], v[162:165], v[198:201], v[20:23]
	v_mfma_f32_16x16x32_bf16 v[16:19], v[170:173], v[198:201], v[16:19]
	v_mfma_f32_16x16x32_bf16 v[4:7], v[162:165], v[218:221], v[4:7]
	v_mfma_f32_16x16x32_bf16 v[0:3], v[170:173], v[218:221], v[0:3]
	v_mfma_f32_16x16x32_bf16 v[52:55], v[166:169], v[186:189], v[52:55]
	v_mfma_f32_16x16x32_bf16 v[48:51], v[178:181], v[186:189], v[48:51]
	v_mfma_f32_16x16x32_bf16 v[36:39], v[166:169], v[194:197], v[36:39]
	v_mfma_f32_16x16x32_bf16 v[32:35], v[178:181], v[194:197], v[32:35]
	v_mfma_f32_16x16x32_bf16 v[20:23], v[166:169], v[202:205], v[20:23]
	v_mfma_f32_16x16x32_bf16 v[16:19], v[178:181], v[202:205], v[16:19]
	v_mfma_f32_16x16x32_bf16 v[4:7], v[166:169], v[222:225], v[4:7]
	s_barrier
	v_mfma_f32_16x16x32_bf16 v[0:3], v[178:181], v[222:225], v[0:3]
	s_setprio 0
	s_add_i32 s50, 0, 0x18000
	v_add_u32_e32 v145, s50, v140
	s_add_i32 s51, 0, 0x1c000
	ds_read_b128 v[146:149], v145
	ds_read_b128 v[150:153], v145 offset:1024
	ds_read_b128 v[154:157], v145 offset:2048
	ds_read_b128 v[158:161], v145 offset:3072
	v_add_u32_e32 v145, s51, v140
	ds_read_b128 v[162:165], v145
	ds_read_b128 v[166:169], v145 offset:1024
	ds_read_b128 v[170:173], v145 offset:2048
	ds_read_b128 v[178:181], v145 offset:3072
	s_add_u32 s26, s26, 0x80000
	s_addc_u32 s27, s27, 0
	s_mov_b32 m0, s36
	ds_read_b128 v[182:185], v143 offset:32768
	ds_read_b128 v[186:189], v143 offset:33792
	ds_read_b128 v[190:193], v143 offset:34816
	ds_read_b128 v[194:197], v143 offset:35840
	ds_read_b128 v[198:201], v143 offset:36864
	ds_read_b128 v[202:205], v143 offset:37888
	ds_read_b128 v[218:221], v143 offset:38912
	ds_read_b128 v[222:225], v143 offset:39936
	global_load_lds_dwordx4 v128, s[26:27]
	s_mov_b32 m0, s37
	s_nop 0
	global_load_lds_dwordx4 v130, s[26:27]
	s_waitcnt vmcnt(8)
	s_waitcnt lgkmcnt(0)
	s_barrier
	s_setprio 1
	s_waitcnt lgkmcnt(0)
	v_mfma_f32_16x16x32_bf16 v[124:127], v[146:149], v[182:185], v[124:127]
	v_mfma_f32_16x16x32_bf16 v[120:123], v[154:157], v[182:185], v[120:123]
	v_mfma_f32_16x16x32_bf16 v[108:111], v[146:149], v[190:193], v[108:111]
	v_mfma_f32_16x16x32_bf16 v[104:107], v[154:157], v[190:193], v[104:107]
	v_mfma_f32_16x16x32_bf16 v[92:95], v[146:149], v[198:201], v[92:95]
	v_mfma_f32_16x16x32_bf16 v[88:91], v[154:157], v[198:201], v[88:91]
	v_mfma_f32_16x16x32_bf16 v[76:79], v[146:149], v[218:221], v[76:79]
	v_mfma_f32_16x16x32_bf16 v[72:75], v[154:157], v[218:221], v[72:75]
	v_mfma_f32_16x16x32_bf16 v[124:127], v[150:153], v[186:189], v[124:127]
	v_mfma_f32_16x16x32_bf16 v[120:123], v[158:161], v[186:189], v[120:123]
	v_mfma_f32_16x16x32_bf16 v[108:111], v[150:153], v[194:197], v[108:111]
	v_mfma_f32_16x16x32_bf16 v[104:107], v[158:161], v[194:197], v[104:107]
	v_mfma_f32_16x16x32_bf16 v[92:95], v[150:153], v[202:205], v[92:95]
	v_mfma_f32_16x16x32_bf16 v[88:91], v[158:161], v[202:205], v[88:91]
	v_mfma_f32_16x16x32_bf16 v[76:79], v[150:153], v[222:225], v[76:79]
	v_mfma_f32_16x16x32_bf16 v[72:75], v[158:161], v[222:225], v[72:75]
	s_setprio 0
	s_setprio 1
	v_mfma_f32_16x16x32_bf16 v[116:119], v[162:165], v[182:185], v[116:119]
	v_mfma_f32_16x16x32_bf16 v[112:115], v[170:173], v[182:185], v[112:115]
	v_mfma_f32_16x16x32_bf16 v[100:103], v[162:165], v[190:193], v[100:103]
	v_mfma_f32_16x16x32_bf16 v[96:99], v[170:173], v[190:193], v[96:99]
	v_mfma_f32_16x16x32_bf16 v[84:87], v[162:165], v[198:201], v[84:87]
	v_mfma_f32_16x16x32_bf16 v[80:83], v[170:173], v[198:201], v[80:83]
	v_mfma_f32_16x16x32_bf16 v[68:71], v[162:165], v[218:221], v[68:71]
	v_mfma_f32_16x16x32_bf16 v[64:67], v[170:173], v[218:221], v[64:67]
	v_mfma_f32_16x16x32_bf16 v[116:119], v[166:169], v[186:189], v[116:119]
	v_mfma_f32_16x16x32_bf16 v[112:115], v[178:181], v[186:189], v[112:115]
	v_mfma_f32_16x16x32_bf16 v[100:103], v[166:169], v[194:197], v[100:103]
	v_mfma_f32_16x16x32_bf16 v[96:99], v[178:181], v[194:197], v[96:99]
	v_mfma_f32_16x16x32_bf16 v[84:87], v[166:169], v[202:205], v[84:87]
	v_mfma_f32_16x16x32_bf16 v[80:83], v[178:181], v[202:205], v[80:83]
	v_mfma_f32_16x16x32_bf16 v[68:71], v[166:169], v[222:225], v[68:71]
	s_barrier
; #define PG8_STAGE(bufoff, gbase, voff) do { _Pragma("unroll") for (int _i = 0; _i < 2; ++_i) \
;         __builtin_amdgcn_global_load_lds((const unsigned*)((const char*)(gbase) + (voff)[_i]), (LAS unsigned*)(lds + (bufoff) + ldsw + _i * 8192), 16, 0, 0); } while (0)
; #define PG8_LDA(dst, b, h) do { _Pragma("unroll") for (int m = 0; m < 4; ++m) _Pragma("unroll") for (int k = 0; k < 2; ++k) dst[m][k] = *(const LAS bf16x8*)(lds + PG8_SA(b, h) + aoff + m * 2048 + k * 1024); } while (0)
; #define PG8_MMA(ai, bj, At, Bt) do { __builtin_amdgcn_s_setprio(1); _Pragma("unroll") for (int m = 0; m < 4; ++m) _Pragma("unroll") for (int n = 0; n < 2; ++n) _Pragma("unroll") for (int k = 0; k < 2; ++k) \
;         acc[ai][bj][m][n] = __builtin_amdgcn_mfma_f32_16x16x32_bf16(Bt[n][k], At[m][k], acc[ai][bj][m][n], 0, 0, 0); __builtin_amdgcn_s_setprio(0); } while (0)
; #define PG8_WAIT_V(n) asm volatile("s_waitcnt vmcnt(" #n ")" ::: "memory")
; #define PG8_WAIT_L(n) asm volatile("s_waitcnt lgkmcnt(" #n ")" ::: "memory")
; #define PG8_BAR __builtin_amdgcn_s_barrier()
; #define PG8_SCHED __builtin_amdgcn_sched_barrier(0)
; template <class Epi, bool KREV = false>
; __device__ __forceinline__ void gemm_phase(LAS unsigned char* lds, const Gemm g, const StaticOrder& S, const Epi& E, int wave_s) {
;     ...
;             PG8_LDA(At, 1, 1); PG8_STAGE(PG8_SB(1, 0), b3, voffB); PG8_STAGE(PG8_SB(1, 1), b3 + bh, voffB); PG8_STAGE(PG8_SA(1, 0), a3, voffA);
;             PG8_WAIT_V(8); PG8_WAIT_L(0); PG8_BAR; PG8_MMA(1, 0, At, B0); PG8_MMA(1, 1, At, B1); PG8_BAR; PG8_SCHED;
;         }
	v_mfma_f32_16x16x32_bf16 v[64:67], v[178:181], v[222:225], v[64:67]
	s_setprio 0
	s_add_i32 s26, s50, s29
	s_mov_b32 m0, s26
	ds_read_b128 v[182:185], v143 offset:49152
	ds_read_b128 v[186:189], v143 offset:50176
	ds_read_b128 v[190:193], v143 offset:51200
	ds_read_b128 v[194:197], v143 offset:52224
	ds_read_b128 v[198:201], v143 offset:53248
	ds_read_b128 v[202:205], v143 offset:54272
	ds_read_b128 v[218:221], v143 offset:55296
	ds_read_b128 v[222:225], v143 offset:56320
	global_load_lds_dwordx4 v176, s[98:99]
	s_add_i32 m0, s26, 0x2000
	s_add_u32 s24, s24, 0x80080
	s_addc_u32 s25, s25, 0
	s_add_i32 s26, s51, s29
	global_load_lds_dwordx4 v132, s[98:99]
	s_mov_b32 m0, s26
	s_nop 0
	global_load_lds_dwordx4 v176, s[24:25]
	s_add_i32 m0, s26, 0x2000
	s_nop 0
	global_load_lds_dwordx4 v132, s[24:25]
	s_mov_b32 m0, s38
	s_nop 0
	global_load_lds_dwordx4 v128, s[100:101]
	v_lshl_add_u64 v[138:139], v[226:227], 0, s[2:3]
	s_mov_b32 m0, s39
	s_nop 0
	global_load_lds_dwordx4 v130, s[100:101]
	s_waitcnt vmcnt(8)
	s_waitcnt lgkmcnt(0)
	s_barrier
	s_setprio 1
	s_waitcnt lgkmcnt(0)
	v_mfma_f32_16x16x32_bf16 v[60:63], v[146:149], v[182:185], v[60:63]
	v_mfma_f32_16x16x32_bf16 v[56:59], v[154:157], v[182:185], v[56:59]
	v_mfma_f32_16x16x32_bf16 v[44:47], v[146:149], v[190:193], v[44:47]
	v_mfma_f32_16x16x32_bf16 v[40:43], v[154:157], v[190:193], v[40:43]
	v_mfma_f32_16x16x32_bf16 v[28:31], v[146:149], v[198:201], v[28:31]
	v_mfma_f32_16x16x32_bf16 v[24:27], v[154:157], v[198:201], v[24:27]
	v_mfma_f32_16x16x32_bf16 v[12:15], v[146:149], v[218:221], v[12:15]
	v_mfma_f32_16x16x32_bf16 v[8:11], v[154:157], v[218:221], v[8:11]
	v_mfma_f32_16x16x32_bf16 v[60:63], v[150:153], v[186:189], v[60:63]
	v_mfma_f32_16x16x32_bf16 v[56:59], v[158:161], v[186:189], v[56:59]
	v_mfma_f32_16x16x32_bf16 v[44:47], v[150:153], v[194:197], v[44:47]
	v_mfma_f32_16x16x32_bf16 v[40:43], v[158:161], v[194:197], v[40:43]
	v_mfma_f32_16x16x32_bf16 v[28:31], v[150:153], v[202:205], v[28:31]
	v_mfma_f32_16x16x32_bf16 v[24:27], v[158:161], v[202:205], v[24:27]
	v_mfma_f32_16x16x32_bf16 v[12:15], v[150:153], v[222:225], v[12:15]
	v_mfma_f32_16x16x32_bf16 v[8:11], v[158:161], v[222:225], v[8:11]
	s_setprio 0
	s_setprio 1
	v_mfma_f32_16x16x32_bf16 v[52:55], v[162:165], v[182:185], v[52:55]
	v_mfma_f32_16x16x32_bf16 v[48:51], v[170:173], v[182:185], v[48:51]
	v_mfma_f32_16x16x32_bf16 v[36:39], v[162:165], v[190:193], v[36:39]
	v_mfma_f32_16x16x32_bf16 v[32:35], v[170:173], v[190:193], v[32:35]
	v_mfma_f32_16x16x32_bf16 v[20:23], v[162:165], v[198:201], v[20:23]
	v_mfma_f32_16x16x32_bf16 v[16:19], v[170:173], v[198:201], v[16:19]
	v_mfma_f32_16x16x32_bf16 v[4:7], v[162:165], v[218:221], v[4:7]
	v_mfma_f32_16x16x32_bf16 v[0:3], v[170:173], v[218:221], v[0:3]
	v_mfma_f32_16x16x32_bf16 v[52:55], v[166:169], v[186:189], v[52:55]
	v_mfma_f32_16x16x32_bf16 v[48:51], v[178:181], v[186:189], v[48:51]
	v_mfma_f32_16x16x32_bf16 v[36:39], v[166:169], v[194:197], v[36:39]
	v_mfma_f32_16x16x32_bf16 v[32:35], v[178:181], v[194:197], v[32:35]
	s_add_i32 s49, s49, 2
	s_add_u32 s22, s22, 0x100
	s_addc_u32 s23, s23, 0
	v_mfma_f32_16x16x32_bf16 v[20:23], v[166:169], v[202:205], v[20:23]
	s_add_u32 s47, s47, 0x100
	s_addc_u32 s48, s48, 0
	v_mfma_f32_16x16x32_bf16 v[16:19], v[178:181], v[202:205], v[16:19]
	s_cmp_gt_u32 s49, 29
	v_mfma_f32_16x16x32_bf16 v[4:7], v[166:169], v[222:225], v[4:7]
	s_barrier
	v_mfma_f32_16x16x32_bf16 v[0:3], v[178:181], v[222:225], v[0:3]
	s_setprio 0
	s_cbranch_scc0 .LBB0_162
	s_and_b64 vcc, exec, s[18:19]
	s_cbranch_vccz .LBB0_165
	s_barrier

; #define PG8_STAGE(bufoff, gbase, voff) do { _Pragma("unroll") for (int _i = 0; _i < 2; ++_i) \
;         __builtin_amdgcn_global_load_lds((const unsigned*)((const char*)(gbase) + (voff)[_i]), (LAS unsigned*)(lds + (bufoff) + ldsw + _i * 8192), 16, 0, 0); } while (0)
; #define PG8_LDA(dst, b, h) do { _Pragma("unroll") for (int m = 0; m < 4; ++m) _Pragma("unroll") for (int k = 0; k < 2; ++k) dst[m][k] = *(const LAS bf16x8*)(lds + PG8_SA(b, h) + aoff + m * 2048 + k * 1024); } while (0)
; #define PG8_LDB(dst, b, h) do { _Pragma("unroll") for (int n = 0; n < 2; ++n) _Pragma("unroll") for (int k = 0; k < 2; ++k) dst[n][k] = *(const LAS bf16x8*)(lds + PG8_SB(b, h) + boff + n * 2048 + k * 1024); } while (0)
; #define PG8_MMA(ai, bj, At, Bt) do { __builtin_amdgcn_s_setprio(1); _Pragma("unroll") for (int m = 0; m < 4; ++m) _Pragma("unroll") for (int n = 0; n < 2; ++n) _Pragma("unroll") for (int k = 0; k < 2; ++k) \
;         acc[ai][bj][m][n] = __builtin_amdgcn_mfma_f32_16x16x32_bf16(Bt[n][k], At[m][k], acc[ai][bj][m][n], 0, 0, 0); __builtin_amdgcn_s_setprio(0); } while (0)
; #define PG8_WAIT_V(n) asm volatile("s_waitcnt vmcnt(" #n ")" ::: "memory")
; #define PG8_WAIT_L(n) asm volatile("s_waitcnt lgkmcnt(" #n ")" ::: "memory")
; #define PG8_BAR __builtin_amdgcn_s_barrier()
; #define PG8_SCHED __builtin_amdgcn_sched_barrier(0)
; template <class Epi, bool KREV = false>
; __device__ __forceinline__ void gemm_phase(LAS unsigned char* lds, const Gemm g, const StaticOrder& S, const Epi& E, int wave_s) {
;     ...
;             PG8_LDB(B0, 0, 0); PG8_LDB(B1, 0, 1); PG8_SCHED; PG8_LDA(At, 0, 0); PG8_STAGE(PG8_SA(1, 1), a1 + hstep, voffA);
;             PG8_WAIT_V(8); PG8_WAIT_L(0); PG8_BAR; PG8_MMA(0, 0, At, B0); PG8_MMA(0, 1, At, B1); PG8_BAR; PG8_SCHED;
;             PG8_LDA(At, 0, 1); PG8_STAGE(PG8_SB(0, 0), b2, voffB); PG8_STAGE(PG8_SB(0, 1), b2 + bh, voffB); PG8_STAGE(PG8_SA(0, 0), a2, voffA);
;             PG8_WAIT_V(8); PG8_WAIT_L(0); PG8_BAR; PG8_MMA(1, 0, At, B0); PG8_MMA(1, 1, At, B1); PG8_BAR; PG8_SCHED;
.LBB0_640:
	s_or_b32 s80, s9, 1
	s_lshl_b64 s[46:47], s[80:81], 7
	s_sub_u32 s27, 0, s46
	s_subb_u32 s45, 0, s47
	s_add_i32 s48, 0, 0x10000
	s_add_i32 s49, 0, 0x14000
	s_add_u32 s46, s41, s27
	s_addc_u32 s47, s42, s45
	s_add_i32 m0, s34, 0xc000
	s_nop 0
	global_load_lds_dwordx4 v156, s[46:47]
	s_add_i32 m0, s34, 0xe000
	s_nop 0
	global_load_lds_dwordx4 v154, s[46:47]
	s_waitcnt vmcnt(8)
	s_waitcnt lgkmcnt(0)
	s_barrier
	s_setprio 1
	s_waitcnt lgkmcnt(0)
	v_mfma_f32_16x16x32_bf16 v[132:135], v[112:115], v[218:221], v[132:135]
	v_mfma_f32_16x16x32_bf16 v[120:123], v[136:139], v[218:221], v[120:123]
	v_mfma_f32_16x16x32_bf16 v[108:111], v[112:115], v[226:229], v[108:111]
	v_mfma_f32_16x16x32_bf16 v[104:107], v[136:139], v[226:229], v[104:107]
	v_mfma_f32_16x16x32_bf16 v[92:95], v[112:115], v[234:237], v[92:95]
	v_mfma_f32_16x16x32_bf16 v[88:91], v[136:139], v[234:237], v[88:91]
	v_mfma_f32_16x16x32_bf16 v[76:79], v[112:115], v[242:245], v[76:79]
	v_mfma_f32_16x16x32_bf16 v[72:75], v[136:139], v[242:245], v[72:75]
	v_mfma_f32_16x16x32_bf16 v[132:135], v[124:127], v[222:225], v[132:135]
	v_mfma_f32_16x16x32_bf16 v[120:123], v[140:143], v[222:225], v[120:123]
	v_mfma_f32_16x16x32_bf16 v[108:111], v[124:127], v[230:233], v[108:111]
	v_mfma_f32_16x16x32_bf16 v[104:107], v[140:143], v[230:233], v[104:107]
	v_mfma_f32_16x16x32_bf16 v[92:95], v[124:127], v[238:241], v[92:95]
	v_mfma_f32_16x16x32_bf16 v[88:91], v[140:143], v[238:241], v[88:91]
	v_mfma_f32_16x16x32_bf16 v[76:79], v[124:127], v[246:249], v[76:79]
	v_mfma_f32_16x16x32_bf16 v[72:75], v[140:143], v[246:249], v[72:75]
	s_setprio 0
	s_setprio 1
	v_mfma_f32_16x16x32_bf16 v[128:131], v[144:147], v[218:221], v[128:131]
	v_mfma_f32_16x16x32_bf16 v[116:119], v[194:197], v[218:221], v[116:119]
	v_mfma_f32_16x16x32_bf16 v[100:103], v[144:147], v[226:229], v[100:103]
	v_mfma_f32_16x16x32_bf16 v[96:99], v[194:197], v[226:229], v[96:99]
	v_mfma_f32_16x16x32_bf16 v[84:87], v[144:147], v[234:237], v[84:87]
	v_mfma_f32_16x16x32_bf16 v[80:83], v[194:197], v[234:237], v[80:83]
	v_mfma_f32_16x16x32_bf16 v[68:71], v[144:147], v[242:245], v[68:71]
	v_mfma_f32_16x16x32_bf16 v[64:67], v[194:197], v[242:245], v[64:67]
	v_mfma_f32_16x16x32_bf16 v[128:131], v[148:151], v[222:225], v[128:131]
	v_mfma_f32_16x16x32_bf16 v[116:119], v[202:205], v[222:225], v[116:119]
	v_mfma_f32_16x16x32_bf16 v[100:103], v[148:151], v[230:233], v[100:103]
	v_mfma_f32_16x16x32_bf16 v[96:99], v[202:205], v[230:233], v[96:99]
	v_mfma_f32_16x16x32_bf16 v[84:87], v[148:151], v[238:241], v[84:87]
	v_mfma_f32_16x16x32_bf16 v[80:83], v[202:205], v[238:241], v[80:83]
	v_mfma_f32_16x16x32_bf16 v[68:71], v[148:151], v[246:249], v[68:71]
	s_barrier
	v_mfma_f32_16x16x32_bf16 v[64:67], v[202:205], v[246:249], v[64:67]
	s_setprio 0
	s_add_u32 s98, s28, s78
	s_addc_u32 s99, s29, s79
	s_add_u32 s100, s30, s78
	s_addc_u32 s101, s31, s79
	s_add_i32 s27, s48, s1
	s_mov_b32 m0, s27
	ds_read_b128 v[218:221], v201 offset:16384
	ds_read_b128 v[222:225], v201 offset:17408
	ds_read_b128 v[226:229], v201 offset:18432
	ds_read_b128 v[230:233], v201 offset:19456
	ds_read_b128 v[234:237], v201 offset:20480
	ds_read_b128 v[238:241], v201 offset:21504
	ds_read_b128 v[242:245], v201 offset:22528
	ds_read_b128 v[246:249], v201 offset:23552
	global_load_lds_dwordx4 v176, s[28:29]
	s_add_i32 m0, s27, 0x2000
	s_add_u32 s46, s28, 0x80000
	s_addc_u32 s47, s29, 0
	s_add_i32 s27, s49, s1
	global_load_lds_dwordx4 v152, s[28:29]
	s_mov_b32 m0, s27
	s_nop 0
	global_load_lds_dwordx4 v176, s[46:47]
	s_add_i32 m0, s27, 0x2000
	s_nop 0
	global_load_lds_dwordx4 v152, s[46:47]
	s_mov_b32 m0, s34
	s_nop 0
	global_load_lds_dwordx4 v156, s[30:31]
	s_mov_b32 m0, s35
	s_nop 0
	global_load_lds_dwordx4 v154, s[30:31]
	s_waitcnt vmcnt(8)
	s_waitcnt lgkmcnt(0)
	s_barrier
	s_setprio 1
	s_waitcnt lgkmcnt(0)
	v_mfma_f32_16x16x32_bf16 v[60:63], v[112:115], v[218:221], v[60:63]
	v_mfma_f32_16x16x32_bf16 v[56:59], v[136:139], v[218:221], v[56:59]
	v_mfma_f32_16x16x32_bf16 v[44:47], v[112:115], v[226:229], v[44:47]
	v_mfma_f32_16x16x32_bf16 v[40:43], v[136:139], v[226:229], v[40:43]
	v_mfma_f32_16x16x32_bf16 v[28:31], v[112:115], v[234:237], v[28:31]
	v_mfma_f32_16x16x32_bf16 v[24:27], v[136:139], v[234:237], v[24:27]
	v_mfma_f32_16x16x32_bf16 v[12:15], v[112:115], v[242:245], v[12:15]
	v_mfma_f32_16x16x32_bf16 v[8:11], v[136:139], v[242:245], v[8:11]
	v_mfma_f32_16x16x32_bf16 v[60:63], v[124:127], v[222:225], v[60:63]
	v_mfma_f32_16x16x32_bf16 v[56:59], v[140:143], v[222:225], v[56:59]
	v_mfma_f32_16x16x32_bf16 v[44:47], v[124:127], v[230:233], v[44:47]
	v_mfma_f32_16x16x32_bf16 v[40:43], v[140:143], v[230:233], v[40:43]
	v_mfma_f32_16x16x32_bf16 v[28:31], v[124:127], v[238:241], v[28:31]
	v_mfma_f32_16x16x32_bf16 v[24:27], v[140:143], v[238:241], v[24:27]
	v_mfma_f32_16x16x32_bf16 v[12:15], v[124:127], v[246:249], v[12:15]
	v_mfma_f32_16x16x32_bf16 v[8:11], v[140:143], v[246:249], v[8:11]
	s_setprio 0
	s_setprio 1
	v_mfma_f32_16x16x32_bf16 v[52:55], v[144:147], v[218:221], v[52:55]
	v_mfma_f32_16x16x32_bf16 v[48:51], v[194:197], v[218:221], v[48:51]
	v_mfma_f32_16x16x32_bf16 v[36:39], v[144:147], v[226:229], v[36:39]
	v_mfma_f32_16x16x32_bf16 v[32:35], v[194:197], v[226:229], v[32:35]
	v_mfma_f32_16x16x32_bf16 v[20:23], v[144:147], v[234:237], v[20:23]
	v_mfma_f32_16x16x32_bf16 v[16:19], v[194:197], v[234:237], v[16:19]
	v_mfma_f32_16x16x32_bf16 v[4:7], v[144:147], v[242:245], v[4:7]
	v_mfma_f32_16x16x32_bf16 v[0:3], v[194:197], v[242:245], v[0:3]
	v_mfma_f32_16x16x32_bf16 v[52:55], v[148:151], v[222:225], v[52:55]
	v_mfma_f32_16x16x32_bf16 v[48:51], v[202:205], v[222:225], v[48:51]
	v_mfma_f32_16x16x32_bf16 v[36:39], v[148:151], v[230:233], v[36:39]
	v_mfma_f32_16x16x32_bf16 v[32:35], v[202:205], v[230:233], v[32:35]
	v_mfma_f32_16x16x32_bf16 v[20:23], v[148:151], v[238:241], v[20:23]
	v_mfma_f32_16x16x32_bf16 v[16:19], v[202:205], v[238:241], v[16:19]
	v_mfma_f32_16x16x32_bf16 v[4:7], v[148:151], v[246:249], v[4:7]
	s_barrier
; #define PG8_STAGE(bufoff, gbase, voff) do { _Pragma("unroll") for (int _i = 0; _i < 2; ++_i) \
;         __builtin_amdgcn_global_load_lds((const unsigned*)((const char*)(gbase) + (voff)[_i]), (LAS unsigned*)(lds + (bufoff) + ldsw + _i * 8192), 16, 0, 0); } while (0)
; #define PG8_LDA(dst, b, h) do { _Pragma("unroll") for (int m = 0; m < 4; ++m) _Pragma("unroll") for (int k = 0; k < 2; ++k) dst[m][k] = *(const LAS bf16x8*)(lds + PG8_SA(b, h) + aoff + m * 2048 + k * 1024); } while (0)
; #define PG8_LDB(dst, b, h) do { _Pragma("unroll") for (int n = 0; n < 2; ++n) _Pragma("unroll") for (int k = 0; k < 2; ++k) dst[n][k] = *(const LAS bf16x8*)(lds + PG8_SB(b, h) + boff + n * 2048 + k * 1024); } while (0)
; #define PG8_MMA(ai, bj, At, Bt) do { __builtin_amdgcn_s_setprio(1); _Pragma("unroll") for (int m = 0; m < 4; ++m) _Pragma("unroll") for (int n = 0; n < 2; ++n) _Pragma("unroll") for (int k = 0; k < 2; ++k) \
;         acc[ai][bj][m][n] = __builtin_amdgcn_mfma_f32_16x16x32_bf16(Bt[n][k], At[m][k], acc[ai][bj][m][n], 0, 0, 0); __builtin_amdgcn_s_setprio(0); } while (0)
; #define PG8_WAIT_V(n) asm volatile("s_waitcnt vmcnt(" #n ")" ::: "memory")
; #define PG8_WAIT_L(n) asm volatile("s_waitcnt lgkmcnt(" #n ")" ::: "memory")
; #define PG8_BAR __builtin_amdgcn_s_barrier()
; #define PG8_SCHED __builtin_amdgcn_sched_barrier(0)
; template <class Epi, bool KREV = false>
; __device__ __forceinline__ void gemm_phase(LAS unsigned char* lds, const Gemm g, const StaticOrder& S, const Epi& E, int wave_s) {
;     ...
;             PG8_LDB(B0, 1, 0); PG8_LDB(B1, 1, 1); PG8_SCHED; PG8_LDA(At, 1, 0); PG8_STAGE(PG8_SA(0, 1), a2 + hstep, voffA);
;             PG8_WAIT_V(8); PG8_WAIT_L(0); PG8_BAR; PG8_MMA(0, 0, At, B0); PG8_MMA(0, 1, At, B1); PG8_BAR; PG8_SCHED;
;             PG8_LDA(At, 1, 1); PG8_STAGE(PG8_SB(1, 0), b3, voffB); PG8_STAGE(PG8_SB(1, 1), b3 + bh, voffB); PG8_STAGE(PG8_SA(1, 0), a3, voffA);
;             PG8_WAIT_V(8); PG8_WAIT_L(0); PG8_BAR; PG8_MMA(1, 0, At, B0); PG8_MMA(1, 1, At, B1); PG8_BAR; PG8_SCHED;
;         }
	v_mfma_f32_16x16x32_bf16 v[0:3], v[202:205], v[246:249], v[0:3]
	s_setprio 0
	s_add_i32 s27, 0, 0x18000
	s_add_i32 s45, 0, 0x1c000
	v_add_u32_e32 v140, s27, v199
	v_add_u32_e32 v202, s45, v199
	ds_read_b128 v[112:115], v140
	ds_read_b128 v[124:127], v140 offset:1024
	ds_read_b128 v[136:139], v140 offset:2048
	ds_read_b128 v[140:143], v140 offset:3072
	ds_read_b128 v[144:147], v202
	ds_read_b128 v[148:151], v202 offset:1024
	ds_read_b128 v[194:197], v202 offset:2048
	ds_read_b128 v[202:205], v202 offset:3072
	s_add_u32 s30, s30, 0x80000
	s_addc_u32 s31, s31, 0
	s_mov_b32 m0, s36
	ds_read_b128 v[218:221], v201 offset:32768
	ds_read_b128 v[222:225], v201 offset:33792
	ds_read_b128 v[226:229], v201 offset:34816
	ds_read_b128 v[230:233], v201 offset:35840
	ds_read_b128 v[234:237], v201 offset:36864
	ds_read_b128 v[238:241], v201 offset:37888
	ds_read_b128 v[242:245], v201 offset:38912
	ds_read_b128 v[246:249], v201 offset:39936
	global_load_lds_dwordx4 v156, s[30:31]
	s_mov_b32 m0, s37
	s_nop 0
	global_load_lds_dwordx4 v154, s[30:31]
	s_waitcnt vmcnt(8)
	s_waitcnt lgkmcnt(0)
	s_barrier
	s_setprio 1
	s_waitcnt lgkmcnt(0)
	v_mfma_f32_16x16x32_bf16 v[132:135], v[112:115], v[218:221], v[132:135]
	v_mfma_f32_16x16x32_bf16 v[120:123], v[136:139], v[218:221], v[120:123]
	v_mfma_f32_16x16x32_bf16 v[108:111], v[112:115], v[226:229], v[108:111]
	v_mfma_f32_16x16x32_bf16 v[104:107], v[136:139], v[226:229], v[104:107]
	v_mfma_f32_16x16x32_bf16 v[92:95], v[112:115], v[234:237], v[92:95]
	v_mfma_f32_16x16x32_bf16 v[88:91], v[136:139], v[234:237], v[88:91]
	v_mfma_f32_16x16x32_bf16 v[76:79], v[112:115], v[242:245], v[76:79]
	v_mfma_f32_16x16x32_bf16 v[72:75], v[136:139], v[242:245], v[72:75]
	v_mfma_f32_16x16x32_bf16 v[132:135], v[124:127], v[222:225], v[132:135]
	v_mfma_f32_16x16x32_bf16 v[120:123], v[140:143], v[222:225], v[120:123]
	v_mfma_f32_16x16x32_bf16 v[108:111], v[124:127], v[230:233], v[108:111]
	v_mfma_f32_16x16x32_bf16 v[104:107], v[140:143], v[230:233], v[104:107]
	v_mfma_f32_16x16x32_bf16 v[92:95], v[124:127], v[238:241], v[92:95]
	v_mfma_f32_16x16x32_bf16 v[88:91], v[140:143], v[238:241], v[88:91]
	v_mfma_f32_16x16x32_bf16 v[76:79], v[124:127], v[246:249], v[76:79]
	v_mfma_f32_16x16x32_bf16 v[72:75], v[140:143], v[246:249], v[72:75]
	s_setprio 0
	s_setprio 1
	v_mfma_f32_16x16x32_bf16 v[128:131], v[144:147], v[218:221], v[128:131]
	v_mfma_f32_16x16x32_bf16 v[116:119], v[194:197], v[218:221], v[116:119]
	v_mfma_f32_16x16x32_bf16 v[100:103], v[144:147], v[226:229], v[100:103]
	v_mfma_f32_16x16x32_bf16 v[96:99], v[194:197], v[226:229], v[96:99]
	v_mfma_f32_16x16x32_bf16 v[84:87], v[144:147], v[234:237], v[84:87]
	v_mfma_f32_16x16x32_bf16 v[80:83], v[194:197], v[234:237], v[80:83]
	v_mfma_f32_16x16x32_bf16 v[68:71], v[144:147], v[242:245], v[68:71]
	v_mfma_f32_16x16x32_bf16 v[64:67], v[194:197], v[242:245], v[64:67]
	v_mfma_f32_16x16x32_bf16 v[128:131], v[148:151], v[222:225], v[128:131]
	v_mfma_f32_16x16x32_bf16 v[116:119], v[202:205], v[222:225], v[116:119]
	v_mfma_f32_16x16x32_bf16 v[100:103], v[148:151], v[230:233], v[100:103]
	v_mfma_f32_16x16x32_bf16 v[96:99], v[202:205], v[230:233], v[96:99]
	v_mfma_f32_16x16x32_bf16 v[84:87], v[148:151], v[238:241], v[84:87]
	v_mfma_f32_16x16x32_bf16 v[80:83], v[202:205], v[238:241], v[80:83]
	v_mfma_f32_16x16x32_bf16 v[68:71], v[148:151], v[246:249], v[68:71]
	s_barrier
	v_mfma_f32_16x16x32_bf16 v[64:67], v[202:205], v[246:249], v[64:67]
	s_setprio 0
	s_add_i32 s27, s27, s1
	s_mov_b32 m0, s27
	ds_read_b128 v[218:221], v201 offset:49152
	ds_read_b128 v[222:225], v201 offset:50176
	ds_read_b128 v[226:229], v201 offset:51200
	ds_read_b128 v[230:233], v201 offset:52224
	ds_read_b128 v[234:237], v201 offset:53248
	ds_read_b128 v[238:241], v201 offset:54272
	ds_read_b128 v[242:245], v201 offset:55296
	ds_read_b128 v[246:249], v201 offset:56320
	global_load_lds_dwordx4 v176, s[98:99]
	s_add_i32 m0, s27, 0x2000
	s_add_u32 s28, s28, 0x7ff80
	s_addc_u32 s29, s29, 0
	s_add_i32 s27, s45, s1
	global_load_lds_dwordx4 v152, s[98:99]
	s_mov_b32 m0, s27
	s_nop 0
	global_load_lds_dwordx4 v176, s[28:29]
	s_add_i32 m0, s27, 0x2000
	s_nop 0
	global_load_lds_dwordx4 v152, s[28:29]
	s_mov_b32 m0, s39
	s_nop 0
	global_load_lds_dwordx4 v156, s[100:101]
	s_mov_b32 m0, s40
	s_nop 0
	global_load_lds_dwordx4 v154, s[100:101]
	s_waitcnt vmcnt(8)
	s_waitcnt lgkmcnt(0)
	s_barrier
	s_setprio 1
	s_waitcnt lgkmcnt(0)
	v_mfma_f32_16x16x32_bf16 v[60:63], v[112:115], v[218:221], v[60:63]
	v_mfma_f32_16x16x32_bf16 v[56:59], v[136:139], v[218:221], v[56:59]
	v_mfma_f32_16x16x32_bf16 v[44:47], v[112:115], v[226:229], v[44:47]
	v_mfma_f32_16x16x32_bf16 v[40:43], v[136:139], v[226:229], v[40:43]
	v_mfma_f32_16x16x32_bf16 v[28:31], v[112:115], v[234:237], v[28:31]
	v_mfma_f32_16x16x32_bf16 v[24:27], v[136:139], v[234:237], v[24:27]
	v_mfma_f32_16x16x32_bf16 v[12:15], v[112:115], v[242:245], v[12:15]
	v_mfma_f32_16x16x32_bf16 v[8:11], v[136:139], v[242:245], v[8:11]
	v_mfma_f32_16x16x32_bf16 v[60:63], v[124:127], v[222:225], v[60:63]
	v_mfma_f32_16x16x32_bf16 v[56:59], v[140:143], v[222:225], v[56:59]
	v_mfma_f32_16x16x32_bf16 v[44:47], v[124:127], v[230:233], v[44:47]
	v_mfma_f32_16x16x32_bf16 v[40:43], v[140:143], v[230:233], v[40:43]
	v_mfma_f32_16x16x32_bf16 v[28:31], v[124:127], v[238:241], v[28:31]
	v_mfma_f32_16x16x32_bf16 v[24:27], v[140:143], v[238:241], v[24:27]
	v_mfma_f32_16x16x32_bf16 v[12:15], v[124:127], v[246:249], v[12:15]
	v_mfma_f32_16x16x32_bf16 v[8:11], v[140:143], v[246:249], v[8:11]
	s_setprio 0
	s_setprio 1
	v_mfma_f32_16x16x32_bf16 v[52:55], v[144:147], v[218:221], v[52:55]
	v_mfma_f32_16x16x32_bf16 v[48:51], v[194:197], v[218:221], v[48:51]
	v_mfma_f32_16x16x32_bf16 v[36:39], v[144:147], v[226:229], v[36:39]
	v_mfma_f32_16x16x32_bf16 v[32:35], v[194:197], v[226:229], v[32:35]
	v_mfma_f32_16x16x32_bf16 v[20:23], v[144:147], v[234:237], v[20:23]
	v_mfma_f32_16x16x32_bf16 v[16:19], v[194:197], v[234:237], v[16:19]
	v_mfma_f32_16x16x32_bf16 v[4:7], v[144:147], v[242:245], v[4:7]
	v_mfma_f32_16x16x32_bf16 v[0:3], v[194:197], v[242:245], v[0:3]
	v_mfma_f32_16x16x32_bf16 v[52:55], v[148:151], v[222:225], v[52:55]
	v_mfma_f32_16x16x32_bf16 v[48:51], v[202:205], v[222:225], v[48:51]
	v_mfma_f32_16x16x32_bf16 v[36:39], v[148:151], v[230:233], v[36:39]
	v_mfma_f32_16x16x32_bf16 v[32:35], v[202:205], v[230:233], v[32:35]
	s_cmp_gt_u32 s9, 29
	s_mov_b32 s9, s26
	v_mfma_f32_16x16x32_bf16 v[20:23], v[148:151], v[238:241], v[20:23]
	v_mfma_f32_16x16x32_bf16 v[16:19], v[202:205], v[238:241], v[16:19]
	v_mfma_f32_16x16x32_bf16 v[4:7], v[148:151], v[246:249], v[4:7]
	s_barrier
	v_mfma_f32_16x16x32_bf16 v[0:3], v[202:205], v[246:249], v[0:3]
	s_setprio 0
	s_cbranch_scc1 .LBB0_645
; #define PG8_STAGE(bufoff, gbase, voff) do { _Pragma("unroll") for (int _i = 0; _i < 2; ++_i) \
;         __builtin_amdgcn_global_load_lds((const unsigned*)((const char*)(gbase) + (voff)[_i]), (LAS unsigned*)(lds + (bufoff) + ldsw + _i * 8192), 16, 0, 0); } while (0)
; #define PG8_LDA(dst, b, h) do { _Pragma("unroll") for (int m = 0; m < 4; ++m) _Pragma("unroll") for (int k = 0; k < 2; ++k) dst[m][k] = *(const LAS bf16x8*)(lds + PG8_SA(b, h) + aoff + m * 2048 + k * 1024); } while (0)
; #define PG8_LDB(dst, b, h) do { _Pragma("unroll") for (int n = 0; n < 2; ++n) _Pragma("unroll") for (int k = 0; k < 2; ++k) dst[n][k] = *(const LAS bf16x8*)(lds + PG8_SB(b, h) + boff + n * 2048 + k * 1024); } while (0)
; #define PG8_SCHED __builtin_amdgcn_sched_barrier(0)
; template <class Epi, bool KREV = false>
; __device__ __forceinline__ void gemm_phase(LAS unsigned char* lds, const Gemm g, const StaticOrder& S, const Epi& E, int wave_s) {
;     ...
;             PG8_LDB(B0, 0, 0); PG8_LDB(B1, 0, 1); PG8_SCHED; PG8_LDA(At, 0, 0); PG8_STAGE(PG8_SA(1, 1), a1 + hstep, voffA);
.Lkr1_reads:
	v_add_u32_e32 v140, 0x10000, v199
	v_add_u32_e32 v202, 0x14000, v199
	ds_read_b128 v[112:115], v140
	ds_read_b128 v[124:127], v140 offset:1024
	ds_read_b128 v[136:139], v140 offset:2048
	ds_read_b128 v[140:143], v140 offset:3072
	ds_read_b128 v[144:147], v202
	ds_read_b128 v[148:151], v202 offset:1024
	ds_read_b128 v[194:197], v202 offset:2048
	ds_read_b128 v[202:205], v202 offset:3072
	ds_read_b128 v[218:221], v201
	ds_read_b128 v[222:225], v201 offset:1024
	ds_read_b128 v[226:229], v201 offset:2048
	ds_read_b128 v[230:233], v201 offset:3072
	ds_read_b128 v[234:237], v201 offset:4096
	ds_read_b128 v[238:241], v201 offset:5120
	ds_read_b128 v[242:245], v201 offset:6144
	ds_read_b128 v[246:249], v201 offset:7168

; #define PG8_STAGE(bufoff, gbase, voff) do { _Pragma("unroll") for (int _i = 0; _i < 2; ++_i) \
;         __builtin_amdgcn_global_load_lds((const unsigned*)((const char*)(gbase) + (voff)[_i]), (LAS unsigned*)(lds + (bufoff) + ldsw + _i * 8192), 16, 0, 0); } while (0)
; #define PG8_LDA(dst, b, h) do { _Pragma("unroll") for (int m = 0; m < 4; ++m) _Pragma("unroll") for (int k = 0; k < 2; ++k) dst[m][k] = *(const LAS bf16x8*)(lds + PG8_SA(b, h) + aoff + m * 2048 + k * 1024); } while (0)
; #define PG8_LDB(dst, b, h) do { _Pragma("unroll") for (int n = 0; n < 2; ++n) _Pragma("unroll") for (int k = 0; k < 2; ++k) dst[n][k] = *(const LAS bf16x8*)(lds + PG8_SB(b, h) + boff + n * 2048 + k * 1024); } while (0)
; #define PG8_MMA(ai, bj, At, Bt) do { __builtin_amdgcn_s_setprio(1); _Pragma("unroll") for (int m = 0; m < 4; ++m) _Pragma("unroll") for (int n = 0; n < 2; ++n) _Pragma("unroll") for (int k = 0; k < 2; ++k) \
;         acc[ai][bj][m][n] = __builtin_amdgcn_mfma_f32_16x16x32_bf16(Bt[n][k], At[m][k], acc[ai][bj][m][n], 0, 0, 0); __builtin_amdgcn_s_setprio(0); } while (0)
; #define PG8_WAIT_V(n) asm volatile("s_waitcnt vmcnt(" #n ")" ::: "memory")
; #define PG8_WAIT_L(n) asm volatile("s_waitcnt lgkmcnt(" #n ")" ::: "memory")
; #define PG8_BAR __builtin_amdgcn_s_barrier()
; #define PG8_SCHED __builtin_amdgcn_sched_barrier(0)
; template <class Epi, bool KREV = false>
; __device__ __forceinline__ void gemm_phase(LAS unsigned char* lds, const Gemm g, const StaticOrder& S, const Epi& E, int wave_s) {
;     ...
;         for (int t = 0; t < nt; t += 2) {
;             const bool last = (t == nt - 2);
;             const char* a1 = cA + (size_t)(t + 1) * kstep;
;             const char* a2 = last ? nA : cA + (size_t)(t + 2) * kstep; const char* b2 = last ? nB : cB + (size_t)(t + 2) * kstep;
;             const char* a3 = a2 + kstep; const char* b3 = b2 + kstep;
;             PG8_LDB(B0, 0, 0); PG8_LDB(B1, 0, 1); PG8_SCHED; PG8_LDA(At, 0, 0); PG8_STAGE(PG8_SA(1, 1), a1 + hstep, voffA);
;             PG8_WAIT_V(8); PG8_WAIT_L(0); PG8_BAR; PG8_MMA(0, 0, At, B0); PG8_MMA(0, 1, At, B1); PG8_BAR; PG8_SCHED;
;             PG8_LDA(At, 0, 1); PG8_STAGE(PG8_SB(0, 0), b2, voffB); PG8_STAGE(PG8_SB(0, 1), b2 + bh, voffB); PG8_STAGE(PG8_SA(0, 0), a2, voffA);
;             PG8_WAIT_V(8); PG8_WAIT_L(0); PG8_BAR; PG8_MMA(1, 0, At, B0); PG8_MMA(1, 1, At, B1); PG8_BAR; PG8_SCHED;
.LBB0_836:
	v_add_u32_e32 v154, 0x10000, v135
	v_add_u32_e32 v170, 0x14000, v135
	ds_read_b128 v[142:145], v154
	ds_read_b128 v[146:149], v154 offset:1024
	ds_read_b128 v[150:153], v154 offset:2048
	ds_read_b128 v[154:157], v154 offset:3072
	ds_read_b128 v[158:161], v170
	ds_read_b128 v[162:165], v170 offset:1024
	ds_read_b128 v[166:169], v170 offset:2048
	ds_read_b128 v[170:173], v170 offset:3072
	ds_read_b128 v[178:181], v194
	ds_read_b128 v[182:185], v194 offset:1024
	ds_read_b128 v[186:189], v194 offset:2048
	ds_read_b128 v[196:199], v194 offset:3072
	ds_read_b128 v[200:203], v194 offset:4096
	ds_read_b128 v[204:207], v194 offset:5120
	ds_read_b128 v[218:221], v194 offset:6144
	ds_read_b128 v[222:225], v194 offset:7168
	s_add_u32 s56, s54, 0xfff80080
	s_addc_u32 s57, s55, -1
	s_add_i32 s84, 0, 0x10000
	s_cmp_eq_u32 s83, 28
	s_cselect_b32 s59, s73, s57
	s_cselect_b32 s58, s74, s56
	s_cselect_b32 s57, s75, s82
	s_cselect_b32 s56, s77, s80
	s_add_i32 s86, 0, 0x14000
	s_add_i32 m0, s19, 0xc000
	s_nop 0
	global_load_lds_dwordx4 v138, s[54:55]
	s_add_i32 m0, s19, 0xe000
	s_nop 0
	global_load_lds_dwordx4 v140, s[54:55]
	s_waitcnt vmcnt(8)
	s_waitcnt lgkmcnt(0)
	s_barrier
	s_setprio 1
	s_waitcnt lgkmcnt(0)
	v_mfma_f32_16x16x32_bf16 v[124:127], v[142:145], v[178:181], v[124:127]
	v_mfma_f32_16x16x32_bf16 v[120:123], v[150:153], v[178:181], v[120:123]
	v_mfma_f32_16x16x32_bf16 v[68:71], v[142:145], v[186:189], v[68:71]
	v_mfma_f32_16x16x32_bf16 v[64:67], v[150:153], v[186:189], v[64:67]
	v_mfma_f32_16x16x32_bf16 v[60:63], v[142:145], v[200:203], v[60:63]
	v_mfma_f32_16x16x32_bf16 v[20:23], v[150:153], v[200:203], v[20:23]
	v_mfma_f32_16x16x32_bf16 v[108:111], v[142:145], v[218:221], v[108:111]
	v_mfma_f32_16x16x32_bf16 v[104:107], v[150:153], v[218:221], v[104:107]
	v_mfma_f32_16x16x32_bf16 v[124:127], v[146:149], v[182:185], v[124:127]
	v_mfma_f32_16x16x32_bf16 v[120:123], v[154:157], v[182:185], v[120:123]
	v_mfma_f32_16x16x32_bf16 v[68:71], v[146:149], v[196:199], v[68:71]
	v_mfma_f32_16x16x32_bf16 v[64:67], v[154:157], v[196:199], v[64:67]
	v_mfma_f32_16x16x32_bf16 v[60:63], v[146:149], v[204:207], v[60:63]
	v_mfma_f32_16x16x32_bf16 v[20:23], v[154:157], v[204:207], v[20:23]
	v_mfma_f32_16x16x32_bf16 v[108:111], v[146:149], v[222:225], v[108:111]
	v_mfma_f32_16x16x32_bf16 v[104:107], v[154:157], v[222:225], v[104:107]
	s_setprio 0
	s_setprio 1
	v_mfma_f32_16x16x32_bf16 v[116:119], v[158:161], v[178:181], v[116:119]
	v_mfma_f32_16x16x32_bf16 v[112:115], v[166:169], v[178:181], v[112:115]
	v_mfma_f32_16x16x32_bf16 v[52:55], v[158:161], v[186:189], v[52:55]
	v_mfma_f32_16x16x32_bf16 v[48:51], v[166:169], v[186:189], v[48:51]
	v_mfma_f32_16x16x32_bf16 v[44:47], v[158:161], v[200:203], v[44:47]
	v_mfma_f32_16x16x32_bf16 v[16:19], v[166:169], v[200:203], v[16:19]
	v_mfma_f32_16x16x32_bf16 v[100:103], v[158:161], v[218:221], v[100:103]
	v_mfma_f32_16x16x32_bf16 v[96:99], v[166:169], v[218:221], v[96:99]
	v_mfma_f32_16x16x32_bf16 v[116:119], v[162:165], v[182:185], v[116:119]
	v_mfma_f32_16x16x32_bf16 v[112:115], v[170:173], v[182:185], v[112:115]
	v_mfma_f32_16x16x32_bf16 v[52:55], v[162:165], v[196:199], v[52:55]
	v_mfma_f32_16x16x32_bf16 v[48:51], v[170:173], v[196:199], v[48:51]
	v_mfma_f32_16x16x32_bf16 v[44:47], v[162:165], v[204:207], v[44:47]
	v_mfma_f32_16x16x32_bf16 v[16:19], v[170:173], v[204:207], v[16:19]
	v_mfma_f32_16x16x32_bf16 v[100:103], v[162:165], v[222:225], v[100:103]
	s_barrier
	v_mfma_f32_16x16x32_bf16 v[96:99], v[170:173], v[222:225], v[96:99]
	s_setprio 0
	s_add_u32 s98, s56, s2
	s_addc_u32 s99, s57, s3
	s_add_u32 s100, s58, s2
	s_addc_u32 s101, s59, s3
	s_add_i32 s84, s84, s66
	s_mov_b32 m0, s84
	ds_read_b128 v[178:181], v194 offset:16384
	ds_read_b128 v[182:185], v194 offset:17408
	ds_read_b128 v[186:189], v194 offset:18432
	ds_read_b128 v[196:199], v194 offset:19456
	ds_read_b128 v[200:203], v194 offset:20480
	ds_read_b128 v[204:207], v194 offset:21504
	ds_read_b128 v[218:221], v194 offset:22528
	ds_read_b128 v[222:225], v194 offset:23552
	global_load_lds_dwordx4 v176, s[56:57]
	s_add_i32 m0, s84, 0x2000
	s_add_u32 s84, s56, 0x1600000
	s_addc_u32 s85, s57, 0
	s_add_i32 s86, s86, s66
	global_load_lds_dwordx4 v132, s[56:57]
	s_mov_b32 m0, s86
	s_nop 0
	global_load_lds_dwordx4 v176, s[84:85]
	s_add_i32 m0, s86, 0x2000
	s_nop 0
	global_load_lds_dwordx4 v132, s[84:85]
	s_mov_b32 m0, s19
	s_nop 0
	global_load_lds_dwordx4 v128, s[58:59]
	s_mov_b32 m0, s21
	s_nop 0
	global_load_lds_dwordx4 v130, s[58:59]
	s_waitcnt vmcnt(8)
	s_waitcnt lgkmcnt(0)
	s_barrier
; #define PG8_STAGE(bufoff, gbase, voff) do { _Pragma("unroll") for (int _i = 0; _i < 2; ++_i) \
;         __builtin_amdgcn_global_load_lds((const unsigned*)((const char*)(gbase) + (voff)[_i]), (LAS unsigned*)(lds + (bufoff) + ldsw + _i * 8192), 16, 0, 0); } while (0)
; #define PG8_LDA(dst, b, h) do { _Pragma("unroll") for (int m = 0; m < 4; ++m) _Pragma("unroll") for (int k = 0; k < 2; ++k) dst[m][k] = *(const LAS bf16x8*)(lds + PG8_SA(b, h) + aoff + m * 2048 + k * 1024); } while (0)
; #define PG8_LDB(dst, b, h) do { _Pragma("unroll") for (int n = 0; n < 2; ++n) _Pragma("unroll") for (int k = 0; k < 2; ++k) dst[n][k] = *(const LAS bf16x8*)(lds + PG8_SB(b, h) + boff + n * 2048 + k * 1024); } while (0)
; #define PG8_MMA(ai, bj, At, Bt) do { __builtin_amdgcn_s_setprio(1); _Pragma("unroll") for (int m = 0; m < 4; ++m) _Pragma("unroll") for (int n = 0; n < 2; ++n) _Pragma("unroll") for (int k = 0; k < 2; ++k) \
;         acc[ai][bj][m][n] = __builtin_amdgcn_mfma_f32_16x16x32_bf16(Bt[n][k], At[m][k], acc[ai][bj][m][n], 0, 0, 0); __builtin_amdgcn_s_setprio(0); } while (0)
; #define PG8_WAIT_V(n) asm volatile("s_waitcnt vmcnt(" #n ")" ::: "memory")
; #define PG8_WAIT_L(n) asm volatile("s_waitcnt lgkmcnt(" #n ")" ::: "memory")
; #define PG8_BAR __builtin_amdgcn_s_barrier()
; #define PG8_SCHED __builtin_amdgcn_sched_barrier(0)
; template <class Epi, bool KREV = false>
; __device__ __forceinline__ void gemm_phase(LAS unsigned char* lds, const Gemm g, const StaticOrder& S, const Epi& E, int wave_s) {
;     ...
;             PG8_WAIT_V(8); PG8_WAIT_L(0); PG8_BAR; PG8_MMA(1, 0, At, B0); PG8_MMA(1, 1, At, B1); PG8_BAR; PG8_SCHED;
;             PG8_LDB(B0, 1, 0); PG8_LDB(B1, 1, 1); PG8_SCHED; PG8_LDA(At, 1, 0); PG8_STAGE(PG8_SA(0, 1), a2 + hstep, voffA);
;             PG8_WAIT_V(8); PG8_WAIT_L(0); PG8_BAR; PG8_MMA(0, 0, At, B0); PG8_MMA(0, 1, At, B1); PG8_BAR; PG8_SCHED;
	s_setprio 1
	s_waitcnt lgkmcnt(0)
	v_mfma_f32_16x16x32_bf16 v[92:95], v[142:145], v[178:181], v[92:95]
	v_mfma_f32_16x16x32_bf16 v[88:91], v[150:153], v[178:181], v[88:91]
	v_mfma_f32_16x16x32_bf16 v[36:39], v[142:145], v[186:189], v[36:39]
	v_mfma_f32_16x16x32_bf16 v[12:15], v[150:153], v[186:189], v[12:15]
	v_mfma_f32_16x16x32_bf16 v[32:35], v[142:145], v[200:203], v[32:35]
	v_mfma_f32_16x16x32_bf16 v[4:7], v[150:153], v[200:203], v[4:7]
	v_mfma_f32_16x16x32_bf16 v[76:79], v[142:145], v[218:221], v[76:79]
	v_mfma_f32_16x16x32_bf16 v[56:59], v[150:153], v[218:221], v[56:59]
	v_mfma_f32_16x16x32_bf16 v[92:95], v[146:149], v[182:185], v[92:95]
	v_mfma_f32_16x16x32_bf16 v[88:91], v[154:157], v[182:185], v[88:91]
	v_mfma_f32_16x16x32_bf16 v[36:39], v[146:149], v[196:199], v[36:39]
	v_mfma_f32_16x16x32_bf16 v[12:15], v[154:157], v[196:199], v[12:15]
	v_mfma_f32_16x16x32_bf16 v[32:35], v[146:149], v[204:207], v[32:35]
	v_mfma_f32_16x16x32_bf16 v[4:7], v[154:157], v[204:207], v[4:7]
	v_mfma_f32_16x16x32_bf16 v[76:79], v[146:149], v[222:225], v[76:79]
	v_mfma_f32_16x16x32_bf16 v[56:59], v[154:157], v[222:225], v[56:59]
	s_setprio 0
	s_setprio 1
	v_mfma_f32_16x16x32_bf16 v[84:87], v[158:161], v[178:181], v[84:87]
	v_mfma_f32_16x16x32_bf16 v[80:83], v[166:169], v[178:181], v[80:83]
	v_mfma_f32_16x16x32_bf16 v[28:31], v[158:161], v[186:189], v[28:31]
	v_mfma_f32_16x16x32_bf16 v[8:11], v[166:169], v[186:189], v[8:11]
	v_mfma_f32_16x16x32_bf16 v[24:27], v[158:161], v[200:203], v[24:27]
	v_mfma_f32_16x16x32_bf16 v[0:3], v[166:169], v[200:203], v[0:3]
	v_mfma_f32_16x16x32_bf16 v[72:75], v[158:161], v[218:221], v[72:75]
	v_mfma_f32_16x16x32_bf16 v[40:43], v[166:169], v[218:221], v[40:43]
	v_mfma_f32_16x16x32_bf16 v[84:87], v[162:165], v[182:185], v[84:87]
	v_mfma_f32_16x16x32_bf16 v[80:83], v[170:173], v[182:185], v[80:83]
	v_mfma_f32_16x16x32_bf16 v[28:31], v[162:165], v[196:199], v[28:31]
	v_mfma_f32_16x16x32_bf16 v[8:11], v[170:173], v[196:199], v[8:11]
	v_mfma_f32_16x16x32_bf16 v[24:27], v[162:165], v[204:207], v[24:27]
	v_mfma_f32_16x16x32_bf16 v[0:3], v[170:173], v[204:207], v[0:3]
	v_mfma_f32_16x16x32_bf16 v[72:75], v[162:165], v[222:225], v[72:75]
	s_barrier
	v_mfma_f32_16x16x32_bf16 v[40:43], v[170:173], v[222:225], v[40:43]
	s_setprio 0
	s_add_i32 s84, 0, 0x18000
	s_add_i32 s85, 0, 0x1c000
	v_add_u32_e32 v154, s84, v135
	v_add_u32_e32 v170, s85, v135
	ds_read_b128 v[142:145], v154
	ds_read_b128 v[146:149], v154 offset:1024
	ds_read_b128 v[150:153], v154 offset:2048
	ds_read_b128 v[154:157], v154 offset:3072
	ds_read_b128 v[158:161], v170
	ds_read_b128 v[162:165], v170 offset:1024
	ds_read_b128 v[166:169], v170 offset:2048
	ds_read_b128 v[170:173], v170 offset:3072
	s_add_u32 s58, s58, 0x80000
	s_addc_u32 s59, s59, 0
	s_mov_b32 m0, s67
	ds_read_b128 v[178:181], v194 offset:32768
	ds_read_b128 v[182:185], v194 offset:33792
	ds_read_b128 v[186:189], v194 offset:34816
	ds_read_b128 v[196:199], v194 offset:35840
	ds_read_b128 v[200:203], v194 offset:36864
	ds_read_b128 v[204:207], v194 offset:37888
	ds_read_b128 v[218:221], v194 offset:38912
	ds_read_b128 v[222:225], v194 offset:39936
	global_load_lds_dwordx4 v128, s[58:59]
	s_mov_b32 m0, s68
	s_nop 0
	global_load_lds_dwordx4 v130, s[58:59]
	s_waitcnt vmcnt(8)
	s_waitcnt lgkmcnt(0)
	s_barrier
	s_setprio 1
	s_waitcnt lgkmcnt(0)
	v_mfma_f32_16x16x32_bf16 v[124:127], v[142:145], v[178:181], v[124:127]
	v_mfma_f32_16x16x32_bf16 v[120:123], v[150:153], v[178:181], v[120:123]
	v_mfma_f32_16x16x32_bf16 v[68:71], v[142:145], v[186:189], v[68:71]
	v_mfma_f32_16x16x32_bf16 v[64:67], v[150:153], v[186:189], v[64:67]
	v_mfma_f32_16x16x32_bf16 v[60:63], v[142:145], v[200:203], v[60:63]
	v_mfma_f32_16x16x32_bf16 v[20:23], v[150:153], v[200:203], v[20:23]
	v_mfma_f32_16x16x32_bf16 v[108:111], v[142:145], v[218:221], v[108:111]
	v_mfma_f32_16x16x32_bf16 v[104:107], v[150:153], v[218:221], v[104:107]
	v_mfma_f32_16x16x32_bf16 v[124:127], v[146:149], v[182:185], v[124:127]
	v_mfma_f32_16x16x32_bf16 v[120:123], v[154:157], v[182:185], v[120:123]
	v_mfma_f32_16x16x32_bf16 v[68:71], v[146:149], v[196:199], v[68:71]
	v_mfma_f32_16x16x32_bf16 v[64:67], v[154:157], v[196:199], v[64:67]
	v_mfma_f32_16x16x32_bf16 v[60:63], v[146:149], v[204:207], v[60:63]
	v_mfma_f32_16x16x32_bf16 v[20:23], v[154:157], v[204:207], v[20:23]
	v_mfma_f32_16x16x32_bf16 v[108:111], v[146:149], v[222:225], v[108:111]
	v_mfma_f32_16x16x32_bf16 v[104:107], v[154:157], v[222:225], v[104:107]
	s_setprio 0
	s_setprio 1
	v_mfma_f32_16x16x32_bf16 v[116:119], v[158:161], v[178:181], v[116:119]
	v_mfma_f32_16x16x32_bf16 v[112:115], v[166:169], v[178:181], v[112:115]
	v_mfma_f32_16x16x32_bf16 v[52:55], v[158:161], v[186:189], v[52:55]
	v_mfma_f32_16x16x32_bf16 v[48:51], v[166:169], v[186:189], v[48:51]
	v_mfma_f32_16x16x32_bf16 v[44:47], v[158:161], v[200:203], v[44:47]
	v_mfma_f32_16x16x32_bf16 v[16:19], v[166:169], v[200:203], v[16:19]
	v_mfma_f32_16x16x32_bf16 v[100:103], v[158:161], v[218:221], v[100:103]
	v_mfma_f32_16x16x32_bf16 v[96:99], v[166:169], v[218:221], v[96:99]
	v_mfma_f32_16x16x32_bf16 v[116:119], v[162:165], v[182:185], v[116:119]
	v_mfma_f32_16x16x32_bf16 v[112:115], v[170:173], v[182:185], v[112:115]
	v_mfma_f32_16x16x32_bf16 v[52:55], v[162:165], v[196:199], v[52:55]
	v_mfma_f32_16x16x32_bf16 v[48:51], v[170:173], v[196:199], v[48:51]
	v_mfma_f32_16x16x32_bf16 v[44:47], v[162:165], v[204:207], v[44:47]
	v_mfma_f32_16x16x32_bf16 v[16:19], v[170:173], v[204:207], v[16:19]
	v_mfma_f32_16x16x32_bf16 v[100:103], v[162:165], v[222:225], v[100:103]
	s_barrier
; #define PG8_STAGE(bufoff, gbase, voff) do { _Pragma("unroll") for (int _i = 0; _i < 2; ++_i) \
;         __builtin_amdgcn_global_load_lds((const unsigned*)((const char*)(gbase) + (voff)[_i]), (LAS unsigned*)(lds + (bufoff) + ldsw + _i * 8192), 16, 0, 0); } while (0)
; #define PG8_LDA(dst, b, h) do { _Pragma("unroll") for (int m = 0; m < 4; ++m) _Pragma("unroll") for (int k = 0; k < 2; ++k) dst[m][k] = *(const LAS bf16x8*)(lds + PG8_SA(b, h) + aoff + m * 2048 + k * 1024); } while (0)
; #define PG8_MMA(ai, bj, At, Bt) do { __builtin_amdgcn_s_setprio(1); _Pragma("unroll") for (int m = 0; m < 4; ++m) _Pragma("unroll") for (int n = 0; n < 2; ++n) _Pragma("unroll") for (int k = 0; k < 2; ++k) \
;         acc[ai][bj][m][n] = __builtin_amdgcn_mfma_f32_16x16x32_bf16(Bt[n][k], At[m][k], acc[ai][bj][m][n], 0, 0, 0); __builtin_amdgcn_s_setprio(0); } while (0)
; #define PG8_WAIT_V(n) asm volatile("s_waitcnt vmcnt(" #n ")" ::: "memory")
; #define PG8_WAIT_L(n) asm volatile("s_waitcnt lgkmcnt(" #n ")" ::: "memory")
; #define PG8_BAR __builtin_amdgcn_s_barrier()
; #define PG8_SCHED __builtin_amdgcn_sched_barrier(0)
; template <class Epi, bool KREV = false>
; __device__ __forceinline__ void gemm_phase(LAS unsigned char* lds, const Gemm g, const StaticOrder& S, const Epi& E, int wave_s) {
;     ...
;             PG8_LDA(At, 1, 1); PG8_STAGE(PG8_SB(1, 0), b3, voffB); PG8_STAGE(PG8_SB(1, 1), b3 + bh, voffB); PG8_STAGE(PG8_SA(1, 0), a3, voffA);
;             PG8_WAIT_V(8); PG8_WAIT_L(0); PG8_BAR; PG8_MMA(1, 0, At, B0); PG8_MMA(1, 1, At, B1); PG8_BAR; PG8_SCHED;
;         }
	v_mfma_f32_16x16x32_bf16 v[96:99], v[170:173], v[222:225], v[96:99]
	s_setprio 0
	s_add_i32 s58, s84, s66
	s_mov_b32 m0, s58
	ds_read_b128 v[178:181], v194 offset:49152
	ds_read_b128 v[182:185], v194 offset:50176
	ds_read_b128 v[186:189], v194 offset:51200
	ds_read_b128 v[196:199], v194 offset:52224
	ds_read_b128 v[200:203], v194 offset:53248
	ds_read_b128 v[204:207], v194 offset:54272
	ds_read_b128 v[218:221], v194 offset:55296
	ds_read_b128 v[222:225], v194 offset:56320
	global_load_lds_dwordx4 v176, s[98:99]
	s_add_i32 m0, s58, 0x2000
	s_add_u32 s56, s56, 0x1600080
	s_addc_u32 s57, s57, 0
	s_add_i32 s58, s85, s66
	global_load_lds_dwordx4 v132, s[98:99]
	s_mov_b32 m0, s58
	s_nop 0
	global_load_lds_dwordx4 v176, s[56:57]
	s_add_i32 m0, s58, 0x2000
	s_nop 0
	global_load_lds_dwordx4 v132, s[56:57]
	s_mov_b32 m0, s70
	s_nop 0
	global_load_lds_dwordx4 v128, s[100:101]
	s_mov_b32 m0, s71
	s_nop 0
	global_load_lds_dwordx4 v130, s[100:101]
	s_waitcnt vmcnt(8)
	s_waitcnt lgkmcnt(0)
	s_barrier
	s_setprio 1
	s_waitcnt lgkmcnt(0)
	v_mfma_f32_16x16x32_bf16 v[92:95], v[142:145], v[178:181], v[92:95]
	v_mfma_f32_16x16x32_bf16 v[88:91], v[150:153], v[178:181], v[88:91]
	v_mfma_f32_16x16x32_bf16 v[36:39], v[142:145], v[186:189], v[36:39]
	v_mfma_f32_16x16x32_bf16 v[12:15], v[150:153], v[186:189], v[12:15]
	v_mfma_f32_16x16x32_bf16 v[32:35], v[142:145], v[200:203], v[32:35]
	v_mfma_f32_16x16x32_bf16 v[4:7], v[150:153], v[200:203], v[4:7]
	v_mfma_f32_16x16x32_bf16 v[76:79], v[142:145], v[218:221], v[76:79]
	v_mfma_f32_16x16x32_bf16 v[56:59], v[150:153], v[218:221], v[56:59]
	v_mfma_f32_16x16x32_bf16 v[92:95], v[146:149], v[182:185], v[92:95]
	v_mfma_f32_16x16x32_bf16 v[88:91], v[154:157], v[182:185], v[88:91]
	v_mfma_f32_16x16x32_bf16 v[36:39], v[146:149], v[196:199], v[36:39]
	v_mfma_f32_16x16x32_bf16 v[12:15], v[154:157], v[196:199], v[12:15]
	v_mfma_f32_16x16x32_bf16 v[32:35], v[146:149], v[204:207], v[32:35]
	v_mfma_f32_16x16x32_bf16 v[4:7], v[154:157], v[204:207], v[4:7]
	v_mfma_f32_16x16x32_bf16 v[76:79], v[146:149], v[222:225], v[76:79]
	v_mfma_f32_16x16x32_bf16 v[56:59], v[154:157], v[222:225], v[56:59]
	s_setprio 0
	s_setprio 1
	v_mfma_f32_16x16x32_bf16 v[84:87], v[158:161], v[178:181], v[84:87]
	v_mfma_f32_16x16x32_bf16 v[80:83], v[166:169], v[178:181], v[80:83]
	v_mfma_f32_16x16x32_bf16 v[28:31], v[158:161], v[186:189], v[28:31]
	v_mfma_f32_16x16x32_bf16 v[8:11], v[166:169], v[186:189], v[8:11]
	v_mfma_f32_16x16x32_bf16 v[24:27], v[158:161], v[200:203], v[24:27]
	v_mfma_f32_16x16x32_bf16 v[0:3], v[166:169], v[200:203], v[0:3]
	v_mfma_f32_16x16x32_bf16 v[72:75], v[158:161], v[218:221], v[72:75]
	v_mfma_f32_16x16x32_bf16 v[40:43], v[166:169], v[218:221], v[40:43]
	v_mfma_f32_16x16x32_bf16 v[84:87], v[162:165], v[182:185], v[84:87]
	v_mfma_f32_16x16x32_bf16 v[80:83], v[170:173], v[182:185], v[80:83]
	v_mfma_f32_16x16x32_bf16 v[28:31], v[162:165], v[196:199], v[28:31]
	v_mfma_f32_16x16x32_bf16 v[8:11], v[170:173], v[196:199], v[8:11]
	s_add_i32 s83, s83, 2
	s_add_u32 s54, s54, 0x100
	s_addc_u32 s55, s55, 0
	v_mfma_f32_16x16x32_bf16 v[24:27], v[162:165], v[204:207], v[24:27]
	s_add_u32 s80, s80, 0x100
	s_addc_u32 s82, s82, 0
	v_mfma_f32_16x16x32_bf16 v[0:3], v[170:173], v[204:207], v[0:3]
	s_cmp_gt_u32 s83, 29
	v_mfma_f32_16x16x32_bf16 v[72:75], v[162:165], v[222:225], v[72:75]
	s_barrier
	v_mfma_f32_16x16x32_bf16 v[40:43], v[170:173], v[222:225], v[40:43]
	s_setprio 0
	s_cbranch_scc0 .LBB0_836
	s_and_b64 vcc, exec, s[38:39]
	s_cbranch_vccz .LBB0_839
	s_barrier

; #define PG8_STAGE(bufoff, gbase, voff) do { _Pragma("unroll") for (int _i = 0; _i < 2; ++_i) \
;         __builtin_amdgcn_global_load_lds((const unsigned*)((const char*)(gbase) + (voff)[_i]), (LAS unsigned*)(lds + (bufoff) + ldsw + _i * 8192), 16, 0, 0); } while (0)
; #define PG8_LDA(dst, b, h) do { _Pragma("unroll") for (int m = 0; m < 4; ++m) _Pragma("unroll") for (int k = 0; k < 2; ++k) dst[m][k] = *(const LAS bf16x8*)(lds + PG8_SA(b, h) + aoff + m * 2048 + k * 1024); } while (0)
; #define PG8_LDB(dst, b, h) do { _Pragma("unroll") for (int n = 0; n < 2; ++n) _Pragma("unroll") for (int k = 0; k < 2; ++k) dst[n][k] = *(const LAS bf16x8*)(lds + PG8_SB(b, h) + boff + n * 2048 + k * 1024); } while (0)
; #define PG8_MMA(ai, bj, At, Bt) do { __builtin_amdgcn_s_setprio(1); _Pragma("unroll") for (int m = 0; m < 4; ++m) _Pragma("unroll") for (int n = 0; n < 2; ++n) _Pragma("unroll") for (int k = 0; k < 2; ++k) \
;         acc[ai][bj][m][n] = __builtin_amdgcn_mfma_f32_16x16x32_bf16(Bt[n][k], At[m][k], acc[ai][bj][m][n], 0, 0, 0); __builtin_amdgcn_s_setprio(0); } while (0)
; #define PG8_WAIT_V(n) asm volatile("s_waitcnt vmcnt(" #n ")" ::: "memory")
; #define PG8_WAIT_L(n) asm volatile("s_waitcnt lgkmcnt(" #n ")" ::: "memory")
; #define PG8_BAR __builtin_amdgcn_s_barrier()
; #define PG8_SCHED __builtin_amdgcn_sched_barrier(0)
; template <class Epi, bool KREV = false>
; __device__ __forceinline__ void gemm_phase(LAS unsigned char* lds, const Gemm g, const StaticOrder& S, const Epi& E, int wave_s) {
;     ...
;             PG8_LDB(B0, 0, 0); PG8_LDB(B1, 0, 1); PG8_SCHED; PG8_LDA(At, 0, 0); PG8_STAGE(PG8_SA(1, 1), a1 + hstep, voffA);
;             PG8_WAIT_V(8); PG8_WAIT_L(0); PG8_BAR; PG8_MMA(0, 0, At, B0); PG8_MMA(0, 1, At, B1); PG8_BAR; PG8_SCHED;
;             PG8_LDA(At, 0, 1); PG8_STAGE(PG8_SB(0, 0), b2, voffB); PG8_STAGE(PG8_SB(0, 1), b2 + bh, voffB); PG8_STAGE(PG8_SA(0, 0), a2, voffA);
;             PG8_WAIT_V(8); PG8_WAIT_L(0); PG8_BAR; PG8_MMA(1, 0, At, B0); PG8_MMA(1, 1, At, B1); PG8_BAR; PG8_SCHED;
.LBB0_1023:
	s_or_b32 s80, s44, 1
	s_lshl_b64 s[46:47], s[80:81], 7
	s_sub_u32 s23, 0, s46
	s_subb_u32 s45, 0, s47
	s_add_i32 s48, 0, 0x10000
	s_add_i32 s49, 0, 0x14000
	s_add_u32 s46, s42, s23
	s_addc_u32 s47, s43, s45
	s_add_i32 m0, s28, 0xc000
	s_nop 0
	global_load_lds_dwordx4 v156, s[46:47]
	s_add_i32 m0, s28, 0xe000
	s_nop 0
	global_load_lds_dwordx4 v154, s[46:47]
	s_waitcnt vmcnt(8)
	s_waitcnt lgkmcnt(0)
	s_barrier
	s_setprio 1
	s_waitcnt lgkmcnt(0)
	v_mfma_f32_16x16x32_bf16 v[132:135], v[112:115], v[218:221], v[132:135]
	v_mfma_f32_16x16x32_bf16 v[120:123], v[136:139], v[218:221], v[120:123]
	v_mfma_f32_16x16x32_bf16 v[108:111], v[112:115], v[226:229], v[108:111]
	v_mfma_f32_16x16x32_bf16 v[104:107], v[136:139], v[226:229], v[104:107]
	v_mfma_f32_16x16x32_bf16 v[92:95], v[112:115], v[234:237], v[92:95]
	v_mfma_f32_16x16x32_bf16 v[88:91], v[136:139], v[234:237], v[88:91]
	v_mfma_f32_16x16x32_bf16 v[76:79], v[112:115], v[242:245], v[76:79]
	v_mfma_f32_16x16x32_bf16 v[72:75], v[136:139], v[242:245], v[72:75]
	v_mfma_f32_16x16x32_bf16 v[132:135], v[124:127], v[222:225], v[132:135]
	v_mfma_f32_16x16x32_bf16 v[120:123], v[140:143], v[222:225], v[120:123]
	v_mfma_f32_16x16x32_bf16 v[108:111], v[124:127], v[230:233], v[108:111]
	v_mfma_f32_16x16x32_bf16 v[104:107], v[140:143], v[230:233], v[104:107]
	v_mfma_f32_16x16x32_bf16 v[92:95], v[124:127], v[238:241], v[92:95]
	v_mfma_f32_16x16x32_bf16 v[88:91], v[140:143], v[238:241], v[88:91]
	v_mfma_f32_16x16x32_bf16 v[76:79], v[124:127], v[246:249], v[76:79]
	v_mfma_f32_16x16x32_bf16 v[72:75], v[140:143], v[246:249], v[72:75]
	s_setprio 0
	s_setprio 1
	v_mfma_f32_16x16x32_bf16 v[128:131], v[144:147], v[218:221], v[128:131]
	v_mfma_f32_16x16x32_bf16 v[116:119], v[194:197], v[218:221], v[116:119]
	v_mfma_f32_16x16x32_bf16 v[100:103], v[144:147], v[226:229], v[100:103]
	v_mfma_f32_16x16x32_bf16 v[96:99], v[194:197], v[226:229], v[96:99]
	v_mfma_f32_16x16x32_bf16 v[84:87], v[144:147], v[234:237], v[84:87]
	v_mfma_f32_16x16x32_bf16 v[80:83], v[194:197], v[234:237], v[80:83]
	v_mfma_f32_16x16x32_bf16 v[68:71], v[144:147], v[242:245], v[68:71]
	v_mfma_f32_16x16x32_bf16 v[64:67], v[194:197], v[242:245], v[64:67]
	v_mfma_f32_16x16x32_bf16 v[128:131], v[148:151], v[222:225], v[128:131]
	v_mfma_f32_16x16x32_bf16 v[116:119], v[202:205], v[222:225], v[116:119]
	v_mfma_f32_16x16x32_bf16 v[100:103], v[148:151], v[230:233], v[100:103]
	v_mfma_f32_16x16x32_bf16 v[96:99], v[202:205], v[230:233], v[96:99]
	v_mfma_f32_16x16x32_bf16 v[84:87], v[148:151], v[238:241], v[84:87]
	v_mfma_f32_16x16x32_bf16 v[80:83], v[202:205], v[238:241], v[80:83]
	v_mfma_f32_16x16x32_bf16 v[68:71], v[148:151], v[246:249], v[68:71]
	s_barrier
	v_mfma_f32_16x16x32_bf16 v[64:67], v[202:205], v[246:249], v[64:67]
	s_setprio 0
	s_add_u32 s98, s24, s78
	s_addc_u32 s99, s25, s79
	s_add_u32 s100, s26, s78
	s_addc_u32 s101, s27, s79
	s_add_i32 s23, s48, s1
	s_mov_b32 m0, s23
	ds_read_b128 v[218:221], v201 offset:16384
	ds_read_b128 v[222:225], v201 offset:17408
	ds_read_b128 v[226:229], v201 offset:18432
	ds_read_b128 v[230:233], v201 offset:19456
	ds_read_b128 v[234:237], v201 offset:20480
	ds_read_b128 v[238:241], v201 offset:21504
	ds_read_b128 v[242:245], v201 offset:22528
	ds_read_b128 v[246:249], v201 offset:23552
	global_load_lds_dwordx4 v176, s[24:25]
	s_add_i32 m0, s23, 0x2000
	s_add_u32 s46, s24, 0x160000
	s_addc_u32 s47, s25, 0
	s_add_i32 s23, s49, s1
	global_load_lds_dwordx4 v152, s[24:25]
	s_mov_b32 m0, s23
	s_nop 0
	global_load_lds_dwordx4 v176, s[46:47]
	s_add_i32 m0, s23, 0x2000
	s_nop 0
	global_load_lds_dwordx4 v152, s[46:47]
	s_mov_b32 m0, s28
	s_nop 0
	global_load_lds_dwordx4 v156, s[26:27]
	s_mov_b32 m0, s29
	s_nop 0
	global_load_lds_dwordx4 v154, s[26:27]
	s_waitcnt vmcnt(8)
	s_waitcnt lgkmcnt(0)
	s_barrier
	s_setprio 1
	s_waitcnt lgkmcnt(0)
	v_mfma_f32_16x16x32_bf16 v[60:63], v[112:115], v[218:221], v[60:63]
	v_mfma_f32_16x16x32_bf16 v[56:59], v[136:139], v[218:221], v[56:59]
	v_mfma_f32_16x16x32_bf16 v[44:47], v[112:115], v[226:229], v[44:47]
	v_mfma_f32_16x16x32_bf16 v[40:43], v[136:139], v[226:229], v[40:43]
	v_mfma_f32_16x16x32_bf16 v[28:31], v[112:115], v[234:237], v[28:31]
	v_mfma_f32_16x16x32_bf16 v[24:27], v[136:139], v[234:237], v[24:27]
	v_mfma_f32_16x16x32_bf16 v[12:15], v[112:115], v[242:245], v[12:15]
	v_mfma_f32_16x16x32_bf16 v[8:11], v[136:139], v[242:245], v[8:11]
	v_mfma_f32_16x16x32_bf16 v[60:63], v[124:127], v[222:225], v[60:63]
	v_mfma_f32_16x16x32_bf16 v[56:59], v[140:143], v[222:225], v[56:59]
	v_mfma_f32_16x16x32_bf16 v[44:47], v[124:127], v[230:233], v[44:47]
	v_mfma_f32_16x16x32_bf16 v[40:43], v[140:143], v[230:233], v[40:43]
	v_mfma_f32_16x16x32_bf16 v[28:31], v[124:127], v[238:241], v[28:31]
	v_mfma_f32_16x16x32_bf16 v[24:27], v[140:143], v[238:241], v[24:27]
	v_mfma_f32_16x16x32_bf16 v[12:15], v[124:127], v[246:249], v[12:15]
	v_mfma_f32_16x16x32_bf16 v[8:11], v[140:143], v[246:249], v[8:11]
	s_setprio 0
	s_setprio 1
	v_mfma_f32_16x16x32_bf16 v[52:55], v[144:147], v[218:221], v[52:55]
	v_mfma_f32_16x16x32_bf16 v[48:51], v[194:197], v[218:221], v[48:51]
	v_mfma_f32_16x16x32_bf16 v[36:39], v[144:147], v[226:229], v[36:39]
	v_mfma_f32_16x16x32_bf16 v[32:35], v[194:197], v[226:229], v[32:35]
	v_mfma_f32_16x16x32_bf16 v[20:23], v[144:147], v[234:237], v[20:23]
	v_mfma_f32_16x16x32_bf16 v[16:19], v[194:197], v[234:237], v[16:19]
	v_mfma_f32_16x16x32_bf16 v[4:7], v[144:147], v[242:245], v[4:7]
	v_mfma_f32_16x16x32_bf16 v[0:3], v[194:197], v[242:245], v[0:3]
	v_mfma_f32_16x16x32_bf16 v[52:55], v[148:151], v[222:225], v[52:55]
	v_mfma_f32_16x16x32_bf16 v[48:51], v[202:205], v[222:225], v[48:51]
	v_mfma_f32_16x16x32_bf16 v[36:39], v[148:151], v[230:233], v[36:39]
	v_mfma_f32_16x16x32_bf16 v[32:35], v[202:205], v[230:233], v[32:35]
	v_mfma_f32_16x16x32_bf16 v[20:23], v[148:151], v[238:241], v[20:23]
	v_mfma_f32_16x16x32_bf16 v[16:19], v[202:205], v[238:241], v[16:19]
	v_mfma_f32_16x16x32_bf16 v[4:7], v[148:151], v[246:249], v[4:7]
	s_barrier
; #define PG8_STAGE(bufoff, gbase, voff) do { _Pragma("unroll") for (int _i = 0; _i < 2; ++_i) \
;         __builtin_amdgcn_global_load_lds((const unsigned*)((const char*)(gbase) + (voff)[_i]), (LAS unsigned*)(lds + (bufoff) + ldsw + _i * 8192), 16, 0, 0); } while (0)
; #define PG8_LDA(dst, b, h) do { _Pragma("unroll") for (int m = 0; m < 4; ++m) _Pragma("unroll") for (int k = 0; k < 2; ++k) dst[m][k] = *(const LAS bf16x8*)(lds + PG8_SA(b, h) + aoff + m * 2048 + k * 1024); } while (0)
; #define PG8_LDB(dst, b, h) do { _Pragma("unroll") for (int n = 0; n < 2; ++n) _Pragma("unroll") for (int k = 0; k < 2; ++k) dst[n][k] = *(const LAS bf16x8*)(lds + PG8_SB(b, h) + boff + n * 2048 + k * 1024); } while (0)
; #define PG8_MMA(ai, bj, At, Bt) do { __builtin_amdgcn_s_setprio(1); _Pragma("unroll") for (int m = 0; m < 4; ++m) _Pragma("unroll") for (int n = 0; n < 2; ++n) _Pragma("unroll") for (int k = 0; k < 2; ++k) \
;         acc[ai][bj][m][n] = __builtin_amdgcn_mfma_f32_16x16x32_bf16(Bt[n][k], At[m][k], acc[ai][bj][m][n], 0, 0, 0); __builtin_amdgcn_s_setprio(0); } while (0)
; #define PG8_WAIT_V(n) asm volatile("s_waitcnt vmcnt(" #n ")" ::: "memory")
; #define PG8_WAIT_L(n) asm volatile("s_waitcnt lgkmcnt(" #n ")" ::: "memory")
; #define PG8_BAR __builtin_amdgcn_s_barrier()
; #define PG8_SCHED __builtin_amdgcn_sched_barrier(0)
; template <class Epi, bool KREV = false>
; __device__ __forceinline__ void gemm_phase(LAS unsigned char* lds, const Gemm g, const StaticOrder& S, const Epi& E, int wave_s) {
;     ...
;             PG8_LDB(B0, 1, 0); PG8_LDB(B1, 1, 1); PG8_SCHED; PG8_LDA(At, 1, 0); PG8_STAGE(PG8_SA(0, 1), a2 + hstep, voffA);
;             PG8_WAIT_V(8); PG8_WAIT_L(0); PG8_BAR; PG8_MMA(0, 0, At, B0); PG8_MMA(0, 1, At, B1); PG8_BAR; PG8_SCHED;
;             PG8_LDA(At, 1, 1); PG8_STAGE(PG8_SB(1, 0), b3, voffB); PG8_STAGE(PG8_SB(1, 1), b3 + bh, voffB); PG8_STAGE(PG8_SA(1, 0), a3, voffA);
;             PG8_WAIT_V(8); PG8_WAIT_L(0); PG8_BAR; PG8_MMA(1, 0, At, B0); PG8_MMA(1, 1, At, B1); PG8_BAR; PG8_SCHED;
;         }
	v_mfma_f32_16x16x32_bf16 v[0:3], v[202:205], v[246:249], v[0:3]
	s_setprio 0
	s_add_i32 s23, 0, 0x18000
	s_add_i32 s45, 0, 0x1c000
	v_add_u32_e32 v140, s23, v199
	v_add_u32_e32 v202, s45, v199
	ds_read_b128 v[112:115], v140
	ds_read_b128 v[124:127], v140 offset:1024
	ds_read_b128 v[136:139], v140 offset:2048
	ds_read_b128 v[140:143], v140 offset:3072
	ds_read_b128 v[144:147], v202
	ds_read_b128 v[148:151], v202 offset:1024
	ds_read_b128 v[194:197], v202 offset:2048
	ds_read_b128 v[202:205], v202 offset:3072
	s_add_u32 s26, s26, 0x160000
	s_addc_u32 s27, s27, 0
	s_mov_b32 m0, s30
	ds_read_b128 v[218:221], v201 offset:32768
	ds_read_b128 v[222:225], v201 offset:33792
	ds_read_b128 v[226:229], v201 offset:34816
	ds_read_b128 v[230:233], v201 offset:35840
	ds_read_b128 v[234:237], v201 offset:36864
	ds_read_b128 v[238:241], v201 offset:37888
	ds_read_b128 v[242:245], v201 offset:38912
	ds_read_b128 v[246:249], v201 offset:39936
	global_load_lds_dwordx4 v156, s[26:27]
	s_mov_b32 m0, s34
	s_nop 0
	global_load_lds_dwordx4 v154, s[26:27]
	s_waitcnt vmcnt(8)
	s_waitcnt lgkmcnt(0)
	s_barrier
	s_setprio 1
	s_waitcnt lgkmcnt(0)
	v_mfma_f32_16x16x32_bf16 v[132:135], v[112:115], v[218:221], v[132:135]
	v_mfma_f32_16x16x32_bf16 v[120:123], v[136:139], v[218:221], v[120:123]
	v_mfma_f32_16x16x32_bf16 v[108:111], v[112:115], v[226:229], v[108:111]
	v_mfma_f32_16x16x32_bf16 v[104:107], v[136:139], v[226:229], v[104:107]
	v_mfma_f32_16x16x32_bf16 v[92:95], v[112:115], v[234:237], v[92:95]
	v_mfma_f32_16x16x32_bf16 v[88:91], v[136:139], v[234:237], v[88:91]
	v_mfma_f32_16x16x32_bf16 v[76:79], v[112:115], v[242:245], v[76:79]
	v_mfma_f32_16x16x32_bf16 v[72:75], v[136:139], v[242:245], v[72:75]
	v_mfma_f32_16x16x32_bf16 v[132:135], v[124:127], v[222:225], v[132:135]
	v_mfma_f32_16x16x32_bf16 v[120:123], v[140:143], v[222:225], v[120:123]
	v_mfma_f32_16x16x32_bf16 v[108:111], v[124:127], v[230:233], v[108:111]
	v_mfma_f32_16x16x32_bf16 v[104:107], v[140:143], v[230:233], v[104:107]
	v_mfma_f32_16x16x32_bf16 v[92:95], v[124:127], v[238:241], v[92:95]
	v_mfma_f32_16x16x32_bf16 v[88:91], v[140:143], v[238:241], v[88:91]
	v_mfma_f32_16x16x32_bf16 v[76:79], v[124:127], v[246:249], v[76:79]
	v_mfma_f32_16x16x32_bf16 v[72:75], v[140:143], v[246:249], v[72:75]
	s_setprio 0
	s_setprio 1
	v_mfma_f32_16x16x32_bf16 v[128:131], v[144:147], v[218:221], v[128:131]
	v_mfma_f32_16x16x32_bf16 v[116:119], v[194:197], v[218:221], v[116:119]
	v_mfma_f32_16x16x32_bf16 v[100:103], v[144:147], v[226:229], v[100:103]
	v_mfma_f32_16x16x32_bf16 v[96:99], v[194:197], v[226:229], v[96:99]
	v_mfma_f32_16x16x32_bf16 v[84:87], v[144:147], v[234:237], v[84:87]
	v_mfma_f32_16x16x32_bf16 v[80:83], v[194:197], v[234:237], v[80:83]
	v_mfma_f32_16x16x32_bf16 v[68:71], v[144:147], v[242:245], v[68:71]
	v_mfma_f32_16x16x32_bf16 v[64:67], v[194:197], v[242:245], v[64:67]
	v_mfma_f32_16x16x32_bf16 v[128:131], v[148:151], v[222:225], v[128:131]
	v_mfma_f32_16x16x32_bf16 v[116:119], v[202:205], v[222:225], v[116:119]
	v_mfma_f32_16x16x32_bf16 v[100:103], v[148:151], v[230:233], v[100:103]
	v_mfma_f32_16x16x32_bf16 v[96:99], v[202:205], v[230:233], v[96:99]
	v_mfma_f32_16x16x32_bf16 v[84:87], v[148:151], v[238:241], v[84:87]
	v_mfma_f32_16x16x32_bf16 v[80:83], v[202:205], v[238:241], v[80:83]
	v_mfma_f32_16x16x32_bf16 v[68:71], v[148:151], v[246:249], v[68:71]
	s_barrier
	v_mfma_f32_16x16x32_bf16 v[64:67], v[202:205], v[246:249], v[64:67]
	s_setprio 0
	s_add_i32 s23, s23, s1
	s_mov_b32 m0, s23
	ds_read_b128 v[218:221], v201 offset:49152
	ds_read_b128 v[222:225], v201 offset:50176
	ds_read_b128 v[226:229], v201 offset:51200
	ds_read_b128 v[230:233], v201 offset:52224
	ds_read_b128 v[234:237], v201 offset:53248
	ds_read_b128 v[238:241], v201 offset:54272
	ds_read_b128 v[242:245], v201 offset:55296
	ds_read_b128 v[246:249], v201 offset:56320
	global_load_lds_dwordx4 v176, s[98:99]
	s_add_i32 m0, s23, 0x2000
	s_add_u32 s24, s24, 0x15ff80
	s_addc_u32 s25, s25, 0
	s_add_i32 s23, s45, s1
	global_load_lds_dwordx4 v152, s[98:99]
	s_mov_b32 m0, s23
	s_nop 0
	global_load_lds_dwordx4 v176, s[24:25]
	s_add_i32 m0, s23, 0x2000
	s_nop 0
	global_load_lds_dwordx4 v152, s[24:25]
	s_mov_b32 m0, s36
	s_nop 0
	global_load_lds_dwordx4 v156, s[100:101]
	s_mov_b32 m0, s37
	s_nop 0
	global_load_lds_dwordx4 v154, s[100:101]
	s_waitcnt vmcnt(8)
	s_waitcnt lgkmcnt(0)
	s_barrier
	s_setprio 1
	s_waitcnt lgkmcnt(0)
	v_mfma_f32_16x16x32_bf16 v[60:63], v[112:115], v[218:221], v[60:63]
	v_mfma_f32_16x16x32_bf16 v[56:59], v[136:139], v[218:221], v[56:59]
	v_mfma_f32_16x16x32_bf16 v[44:47], v[112:115], v[226:229], v[44:47]
	v_mfma_f32_16x16x32_bf16 v[40:43], v[136:139], v[226:229], v[40:43]
	v_mfma_f32_16x16x32_bf16 v[28:31], v[112:115], v[234:237], v[28:31]
	v_mfma_f32_16x16x32_bf16 v[24:27], v[136:139], v[234:237], v[24:27]
	v_mfma_f32_16x16x32_bf16 v[12:15], v[112:115], v[242:245], v[12:15]
	v_mfma_f32_16x16x32_bf16 v[8:11], v[136:139], v[242:245], v[8:11]
	v_mfma_f32_16x16x32_bf16 v[60:63], v[124:127], v[222:225], v[60:63]
	v_mfma_f32_16x16x32_bf16 v[56:59], v[140:143], v[222:225], v[56:59]
	v_mfma_f32_16x16x32_bf16 v[44:47], v[124:127], v[230:233], v[44:47]
	v_mfma_f32_16x16x32_bf16 v[40:43], v[140:143], v[230:233], v[40:43]
	v_mfma_f32_16x16x32_bf16 v[28:31], v[124:127], v[238:241], v[28:31]
	v_mfma_f32_16x16x32_bf16 v[24:27], v[140:143], v[238:241], v[24:27]
	v_mfma_f32_16x16x32_bf16 v[12:15], v[124:127], v[246:249], v[12:15]
	v_mfma_f32_16x16x32_bf16 v[8:11], v[140:143], v[246:249], v[8:11]
	s_setprio 0
	s_setprio 1
	v_mfma_f32_16x16x32_bf16 v[52:55], v[144:147], v[218:221], v[52:55]
	v_mfma_f32_16x16x32_bf16 v[48:51], v[194:197], v[218:221], v[48:51]
	v_mfma_f32_16x16x32_bf16 v[36:39], v[144:147], v[226:229], v[36:39]
	v_mfma_f32_16x16x32_bf16 v[32:35], v[194:197], v[226:229], v[32:35]
	v_mfma_f32_16x16x32_bf16 v[20:23], v[144:147], v[234:237], v[20:23]
	v_mfma_f32_16x16x32_bf16 v[16:19], v[194:197], v[234:237], v[16:19]
	v_mfma_f32_16x16x32_bf16 v[4:7], v[144:147], v[242:245], v[4:7]
	v_mfma_f32_16x16x32_bf16 v[0:3], v[194:197], v[242:245], v[0:3]
	v_mfma_f32_16x16x32_bf16 v[52:55], v[148:151], v[222:225], v[52:55]
	v_mfma_f32_16x16x32_bf16 v[48:51], v[202:205], v[222:225], v[48:51]
	v_mfma_f32_16x16x32_bf16 v[36:39], v[148:151], v[230:233], v[36:39]
	v_mfma_f32_16x16x32_bf16 v[32:35], v[202:205], v[230:233], v[32:35]
	s_cmpk_gt_u32 s44, 0x55
	s_mov_b32 s44, s22
	v_mfma_f32_16x16x32_bf16 v[20:23], v[148:151], v[238:241], v[20:23]
	v_mfma_f32_16x16x32_bf16 v[16:19], v[202:205], v[238:241], v[16:19]
	v_mfma_f32_16x16x32_bf16 v[4:7], v[148:151], v[246:249], v[4:7]
	s_barrier
	v_mfma_f32_16x16x32_bf16 v[0:3], v[202:205], v[246:249], v[0:3]
	s_setprio 0
	s_cbranch_scc1 .LBB0_1028
